# combination: epilogue load hoist, serpentine MFMA order, accumulator zeroing removed, dynamic-row atomic wait deferred, non-temporal hints on read-once streams
# speedup vs baseline: 1.0133x; 1.0090x over previous
.LBB0_481:
	s_or_b64 exec, exec, s[0:1]
	s_ashr_i32 s39, s38, 31
	s_lshl_b64 s[0:1], s[38:39], 13
	v_lshl_add_u64 v[8:9], v[68:69], 0, s[0:1]
	global_load_dwordx2 v[10:11], v[8:9], off
	global_load_dwordx2 v[12:13], v[8:9], off offset:512
	global_load_dwordx2 v[14:15], v[8:9], off offset:1024
	global_load_dwordx2 v[16:17], v[8:9], off offset:1536
	global_load_dwordx2 v[18:19], v[8:9], off offset:2048
	global_load_dwordx2 v[20:21], v[8:9], off offset:2560
	global_load_dwordx2 v[22:23], v[8:9], off offset:3072
	global_load_dwordx2 v[24:25], v[8:9], off offset:3584
	s_lshl_b64 s[8:9], s[38:39], 14
	v_add_co_u32_e32 v8, vcc, 0x1000, v8
	v_lshl_add_u64 v[6:7], v[70:71], 0, s[8:9]
	s_nop 0
	v_addc_co_u32_e32 v9, vcc, 0, v9, vcc
	global_load_dwordx4 v[2:5], v[6:7], off nt
	global_load_dwordx2 v[26:27], v[8:9], off
	global_load_dwordx2 v[28:29], v[8:9], off offset:512
	global_load_dwordx2 v[30:31], v[8:9], off offset:1024
	global_load_dwordx2 v[32:33], v[8:9], off offset:1536
	global_load_dwordx2 v[34:35], v[8:9], off offset:2048
	global_load_dwordx2 v[36:37], v[8:9], off offset:2560
	global_load_dwordx2 v[38:39], v[8:9], off offset:3072
	s_nop 0
	global_load_dwordx2 v[8:9], v[8:9], off offset:3584
	s_nop 0
	global_load_dwordx4 v[62:65], v[6:7], off offset:1024 nt
	global_load_dwordx4 v[54:57], v[6:7], off offset:2048 nt
	global_load_dwordx4 v[50:53], v[6:7], off offset:3072 nt
	s_waitcnt vmcnt(19)
	v_readfirstlane_b32 s98, v223
	s_nop 1
	v_mov_b32_e32 v83, s98
	v_and_b32_e32 v89, 0xffff0000, v10
	v_and_b32_e32 v91, 0xffff0000, v11
	s_waitcnt vmcnt(18)
	v_and_b32_e32 v95, 0xffff0000, v12
	v_and_b32_e32 v97, 0xffff0000, v13
	v_lshlrev_b32_e32 v88, 16, v10
	v_lshlrev_b32_e32 v90, 16, v11
	v_lshlrev_b32_e32 v94, 16, v12
	v_lshlrev_b32_e32 v96, 16, v13
	s_waitcnt vmcnt(17)
	v_and_b32_e32 v99, 0xffff0000, v14
	v_and_b32_e32 v101, 0xffff0000, v15
	v_mul_f32_e32 v10, v89, v89
	v_mul_f32_e32 v11, v91, v91
	v_mul_f32_e32 v12, v95, v95
	v_mul_f32_e32 v13, v97, v97
	v_lshlrev_b32_e32 v98, 16, v14
	v_lshlrev_b32_e32 v100, 16, v15
	s_waitcnt vmcnt(16)
	v_and_b32_e32 v103, 0xffff0000, v16
	v_and_b32_e32 v105, 0xffff0000, v17
	v_mul_f32_e32 v14, v99, v99
	v_mul_f32_e32 v15, v101, v101
	v_fmac_f32_e32 v10, v88, v88
	v_fmac_f32_e32 v11, v90, v90
	v_fmac_f32_e32 v12, v94, v94
	v_fmac_f32_e32 v13, v96, v96
	v_lshlrev_b32_e32 v102, 16, v16
	v_lshlrev_b32_e32 v104, 16, v17
	s_waitcnt vmcnt(15)
	v_and_b32_e32 v107, 0xffff0000, v18
	v_and_b32_e32 v109, 0xffff0000, v19
	v_mul_f32_e32 v16, v103, v103
	v_mul_f32_e32 v17, v105, v105
	v_fmac_f32_e32 v14, v98, v98
	v_fmac_f32_e32 v15, v100, v100
	v_add_f32_e32 v10, v10, v11
	v_add_f32_e32 v11, v12, v13
	v_lshlrev_b32_e32 v106, 16, v18
	v_lshlrev_b32_e32 v108, 16, v19
	s_waitcnt vmcnt(14)
	v_and_b32_e32 v111, 0xffff0000, v20
	v_and_b32_e32 v113, 0xffff0000, v21
	v_mul_f32_e32 v18, v107, v107
	v_mul_f32_e32 v19, v109, v109
	v_fmac_f32_e32 v16, v102, v102
	v_fmac_f32_e32 v17, v104, v104
	v_add_f32_e32 v12, v14, v15
	v_add_f32_e32 v10, v10, v11
	v_lshlrev_b32_e32 v110, 16, v20
	v_lshlrev_b32_e32 v112, 16, v21
	s_waitcnt vmcnt(13)
	v_and_b32_e32 v115, 0xffff0000, v22
	v_and_b32_e32 v117, 0xffff0000, v23
	v_mul_f32_e32 v20, v111, v111
	v_mul_f32_e32 v21, v113, v113
	v_fmac_f32_e32 v18, v106, v106
	v_fmac_f32_e32 v19, v108, v108
	v_add_f32_e32 v13, v16, v17
	v_add_f32_e32 v10, v10, v12
	v_lshlrev_b32_e32 v114, 16, v22
	v_lshlrev_b32_e32 v116, 16, v23
	v_mul_f32_e32 v22, v115, v115
	v_fmac_f32_e32 v20, v110, v110
	v_fmac_f32_e32 v21, v112, v112
	v_add_f32_e32 v14, v18, v19
	v_add_f32_e32 v10, v10, v13
	v_mul_f32_e32 v11, v117, v117
	v_fmac_f32_e32 v22, v114, v114
	v_add_f32_e32 v15, v20, v21
	v_add_f32_e32 v10, v10, v14
	v_fmac_f32_e32 v11, v116, v116
	v_add_f32_e32 v10, v10, v15
	v_add_f32_e32 v11, v22, v11
	s_waitcnt vmcnt(12)
	v_and_b32_e32 v119, 0xffff0000, v24
	v_and_b32_e32 v121, 0xffff0000, v25
	v_add_f32_e32 v10, v10, v11
	v_lshlrev_b32_e32 v118, 16, v24
	v_lshlrev_b32_e32 v120, 16, v25
	v_mul_f32_e32 v11, v119, v119
	v_mul_f32_e32 v12, v121, v121
	v_fmac_f32_e32 v11, v118, v118
	v_fmac_f32_e32 v12, v120, v120
	v_add_f32_e32 v11, v11, v12
	s_waitcnt vmcnt(10)
	v_and_b32_e32 v123, 0xffff0000, v26
	v_and_b32_e32 v125, 0xffff0000, v27
	v_add_f32_e32 v10, v10, v11
	v_lshlrev_b32_e32 v122, 16, v26
	v_lshlrev_b32_e32 v124, 16, v27
	v_mul_f32_e32 v11, v123, v123
	v_mul_f32_e32 v12, v125, v125
	v_fmac_f32_e32 v11, v122, v122
	v_fmac_f32_e32 v12, v124, v124
	v_add_f32_e32 v11, v11, v12
	s_waitcnt vmcnt(9)
	v_and_b32_e32 v127, 0xffff0000, v28
	v_and_b32_e32 v129, 0xffff0000, v29
	v_add_f32_e32 v10, v10, v11
	v_lshlrev_b32_e32 v126, 16, v28
	v_lshlrev_b32_e32 v128, 16, v29
	v_mul_f32_e32 v11, v127, v127
	v_mul_f32_e32 v12, v129, v129
	v_fmac_f32_e32 v11, v126, v126
	v_fmac_f32_e32 v12, v128, v128
	v_add_f32_e32 v11, v11, v12
	s_waitcnt vmcnt(8)
	v_and_b32_e32 v131, 0xffff0000, v30
	v_and_b32_e32 v133, 0xffff0000, v31
	v_add_f32_e32 v10, v10, v11
	v_lshlrev_b32_e32 v130, 16, v30
	v_lshlrev_b32_e32 v132, 16, v31
	v_mul_f32_e32 v11, v131, v131
	v_mul_f32_e32 v12, v133, v133
	v_fmac_f32_e32 v11, v130, v130
	v_fmac_f32_e32 v12, v132, v132
	v_add_f32_e32 v11, v11, v12
	s_waitcnt vmcnt(7)
	v_and_b32_e32 v135, 0xffff0000, v32
	v_and_b32_e32 v137, 0xffff0000, v33
	v_add_f32_e32 v10, v10, v11
	v_lshlrev_b32_e32 v134, 16, v32
	v_lshlrev_b32_e32 v136, 16, v33
	v_mul_f32_e32 v11, v135, v135
	v_mul_f32_e32 v12, v137, v137
	v_fmac_f32_e32 v11, v134, v134
	v_fmac_f32_e32 v12, v136, v136
	v_add_f32_e32 v11, v11, v12
	s_waitcnt vmcnt(6)
	v_and_b32_e32 v139, 0xffff0000, v34
	v_and_b32_e32 v141, 0xffff0000, v35
	v_add_f32_e32 v10, v10, v11
	v_lshlrev_b32_e32 v138, 16, v34
	v_lshlrev_b32_e32 v140, 16, v35
	v_mul_f32_e32 v11, v139, v139
	v_mul_f32_e32 v12, v141, v141
	v_fmac_f32_e32 v11, v138, v138
	v_fmac_f32_e32 v12, v140, v140
	v_add_f32_e32 v11, v11, v12
	s_waitcnt vmcnt(5)
	v_and_b32_e32 v143, 0xffff0000, v36
	v_and_b32_e32 v145, 0xffff0000, v37
	v_add_f32_e32 v10, v10, v11
	v_lshlrev_b32_e32 v142, 16, v36
	v_lshlrev_b32_e32 v144, 16, v37
	v_mul_f32_e32 v11, v143, v143
	v_mul_f32_e32 v12, v145, v145
	v_fmac_f32_e32 v11, v142, v142
	v_fmac_f32_e32 v12, v144, v144
	v_add_f32_e32 v11, v11, v12
	s_waitcnt vmcnt(4)
	v_and_b32_e32 v148, 0xffff0000, v38
	v_and_b32_e32 v150, 0xffff0000, v39
	v_add_f32_e32 v10, v10, v11
	v_lshlrev_b32_e32 v147, 16, v38
	v_lshlrev_b32_e32 v149, 16, v39
	v_mul_f32_e32 v11, v148, v148
	v_mul_f32_e32 v12, v150, v150
	s_waitcnt vmcnt(3)
	v_and_b32_e32 v152, 0xffff0000, v8
	v_and_b32_e32 v154, 0xffff0000, v9
	v_fmac_f32_e32 v11, v147, v147
	v_fmac_f32_e32 v12, v149, v149
	v_lshlrev_b32_e32 v151, 16, v8
	v_lshlrev_b32_e32 v153, 16, v9
	v_mul_f32_e32 v8, v152, v152
	v_mul_f32_e32 v9, v154, v154
	v_add_f32_e32 v11, v11, v12
	v_fmac_f32_e32 v8, v151, v151
	v_fmac_f32_e32 v9, v153, v153
	v_add_f32_e32 v10, v10, v11
	v_add_f32_e32 v8, v8, v9
	v_add_f32_e32 v8, v10, v8
	ds_bpermute_b32 v9, v1, v8
	s_waitcnt lgkmcnt(0)
	v_add_f32_e32 v8, v8, v9
	ds_bpermute_b32 v9, v76, v8
	s_waitcnt lgkmcnt(0)
	v_add_f32_e32 v10, v8, v9
	ds_bpermute_b32 v11, v77, v10
	v_add_co_u32_e32 v8, vcc, s47, v6
	s_waitcnt lgkmcnt(0)
	v_add_f32_e32 v10, v10, v11
	ds_bpermute_b32 v11, v78, v10
	v_addc_co_u32_e32 v9, vcc, 0, v7, vcc
	v_add_co_u32_e32 v58, vcc, s48, v6
	s_waitcnt lgkmcnt(0)
	v_add_f32_e32 v10, v10, v11
	ds_bpermute_b32 v11, v79, v10
	v_addc_co_u32_e32 v59, vcc, 0, v7, vcc
	v_add_co_u32_e32 v6, vcc, s49, v6
	s_waitcnt lgkmcnt(0)
	v_add_f32_e32 v10, v10, v11
	ds_bpermute_b32 v11, v80, v10
	global_load_dwordx4 v[46:49], v[8:9], off offset:1024 nt
	global_load_dwordx4 v[38:41], v[8:9], off offset:2048 nt
	global_load_dwordx4 v[34:37], v[58:59], off nt
	global_load_dwordx4 v[30:33], v[58:59], off offset:1024 nt
	global_load_dwordx4 v[26:29], v[58:59], off offset:2048 nt
	global_load_dwordx4 v[22:25], v[58:59], off offset:3072 nt
	v_addc_co_u32_e32 v7, vcc, 0, v7, vcc
	global_load_dwordx4 v[42:45], v[8:9], off offset:3072 nt
	global_load_dwordx4 v[18:21], v[6:7], off nt
	s_waitcnt lgkmcnt(0)
	v_add_f32_e32 v8, v10, v11
	v_fmamk_f32 v8, v8, 0x39800000, v66
	v_mul_f32_e32 v9, 0x4f800000, v8
	v_cmp_gt_f32_e32 vcc, s50, v8
	s_nop 1
	v_cndmask_b32_e32 v84, v8, v9, vcc
	global_load_dwordx4 v[14:17], v[6:7], off offset:1024 nt
	global_load_dwordx4 v[10:13], v[6:7], off offset:2048 nt
	s_nop 0
	global_load_dwordx4 v[58:61], v[58:59], off offset:-4096 nt
	s_nop 0
	global_load_dwordx4 v[6:9], v[6:7], off offset:3072 nt
	v_sqrt_f32_e32 v85, v84
	s_nop 0
	v_add_u32_e32 v86, -1, v85
	v_fma_f32 v87, -v86, v85, v84
	v_cmp_ge_f32_e64 s[8:9], 0, v87
	v_add_u32_e32 v87, 1, v85
	s_nop 0
	v_cndmask_b32_e64 v86, v85, v86, s[8:9]
	v_fma_f32 v85, -v87, v85, v84
	v_cmp_lt_f32_e64 s[8:9], 0, v85
	s_nop 1
	v_cndmask_b32_e64 v85, v86, v87, s[8:9]
	v_mul_f32_e32 v86, 0x37800000, v85
	v_cndmask_b32_e32 v85, v85, v86, vcc
	v_cmp_class_f32_e32 vcc, v84, v82
	s_nop 1
	v_cndmask_b32_e32 v92, v85, v84, vcc
	v_div_scale_f32 v84, s[8:9], v92, v92, 0.5
	v_rcp_f32_e32 v93, v84
	s_nop 0
	v_fma_f32 v85, -v84, v93, 1.0
	v_fmac_f32_e32 v93, v85, v93
	v_div_scale_f32 v85, vcc, 0.5, v92, 0.5
	v_mul_f32_e32 v155, v85, v93
	v_fma_f32 v86, -v84, v155, v85
	v_fmac_f32_e32 v155, v86, v93
	v_fma_f32 v156, -v84, v155, v85
	ds_read_b128 v[84:87], v81
	v_div_fmas_f32 v93, v156, v93, v155
	v_div_fixup_f32 v155, v93, v92, 0.5
	v_mul_f32_e32 v88, v155, v88
	v_lshl_add_u64 v[92:93], v[72:73], 0, s[0:1]
	s_waitcnt lgkmcnt(0)
	v_fma_f32 v2, v84, v88, v2
	v_mul_f32_e32 v84, v155, v89
	v_fma_f32 v3, v85, v84, v3
	v_mul_f32_e32 v84, v155, v90
	v_fma_f32 v4, v86, v84, v4
	v_mul_f32_e32 v84, v155, v91
	v_fmac_f32_e32 v5, v87, v84
	v_cvt_pk_bf16_f32 v88, v2, v3
	v_cvt_pk_bf16_f32 v89, v4, v5
	ds_read_b128 v[84:87], v81 offset:1024
	global_store_dwordx2 v[92:93], v[88:89], off
	v_mul_f32_e32 v88, v155, v94
	s_waitcnt vmcnt(15) lgkmcnt(0)
	v_fma_f32 v84, v84, v88, v62
	v_mul_f32_e32 v62, v155, v95
	v_fma_f32 v63, v85, v62, v63
	v_mul_f32_e32 v62, v155, v96
	v_fma_f32 v62, v86, v62, v64
	v_mul_f32_e32 v64, v155, v97
	v_fmac_f32_e32 v65, v87, v64
	v_cvt_pk_bf16_f32 v90, v84, v63
	v_cvt_pk_bf16_f32 v91, v62, v65
	ds_read_b128 v[86:89], v81 offset:2048
	v_mul_f32_e32 v64, v155, v98
	global_store_dwordx2 v[92:93], v[90:91], off offset:512
	s_waitcnt vmcnt(15) lgkmcnt(0)
	v_fma_f32 v54, v64, v86, v54
	v_mul_f32_e32 v64, v155, v99
	v_fma_f32 v55, v64, v87, v55
	v_mul_f32_e32 v64, v155, v100
	v_fma_f32 v56, v64, v88, v56
	v_mul_f32_e32 v64, v155, v101
	v_fmac_f32_e32 v57, v64, v89
	v_cvt_pk_bf16_f32 v90, v54, v55
	v_cvt_pk_bf16_f32 v91, v56, v57
	ds_read_b128 v[86:89], v81 offset:3072
	v_mul_f32_e32 v64, v155, v102
	global_store_dwordx2 v[92:93], v[90:91], off offset:1024
	s_waitcnt vmcnt(15) lgkmcnt(0)
	v_fma_f32 v64, v64, v86, v50
	v_mul_f32_e32 v50, v155, v103
	v_fma_f32 v85, v50, v87, v51
	v_mul_f32_e32 v50, v155, v104
	v_fma_f32 v86, v50, v88, v52
	v_mul_f32_e32 v50, v155, v105
	v_fmac_f32_e32 v53, v50, v89
	v_cvt_pk_bf16_f32 v50, v64, v85
	v_cvt_pk_bf16_f32 v51, v86, v53
	global_store_dwordx2 v[92:93], v[50:51], off offset:1536
	ds_read_b128 v[88:91], v81 offset:4096
	v_mul_f32_e32 v50, v155, v106
	v_mul_f32_e32 v51, v155, v107
	v_mul_f32_e32 v52, v155, v108
	s_waitcnt vmcnt(5) lgkmcnt(0)
	v_fma_f32 v50, v50, v88, v58
	v_mul_f32_e32 v58, v155, v109
	v_fma_f32 v51, v51, v89, v59
	v_fma_f32 v52, v52, v90, v60
	v_fmac_f32_e32 v61, v58, v91
	v_cvt_pk_bf16_f32 v58, v50, v51
	v_cvt_pk_bf16_f32 v59, v52, v61
	ds_read_b128 v[88:91], v81 offset:5120
	global_store_dwordx2 v[92:93], v[58:59], off offset:2048
	v_mul_f32_e32 v58, v155, v110
	s_waitcnt lgkmcnt(0)
	v_fma_f32 v58, v58, v88, v46
	v_mul_f32_e32 v46, v155, v111
	v_fma_f32 v47, v46, v89, v47
	v_mul_f32_e32 v46, v155, v112
	v_fma_f32 v46, v46, v90, v48
	v_mul_f32_e32 v48, v155, v113
	v_fmac_f32_e32 v49, v48, v91
	v_cvt_pk_bf16_f32 v94, v58, v47
	v_cvt_pk_bf16_f32 v95, v46, v49
	ds_read_b128 v[88:91], v81 offset:6144
	v_mul_f32_e32 v48, v155, v114
	global_store_dwordx2 v[92:93], v[94:95], off offset:2560
	s_waitcnt lgkmcnt(0)
	v_fma_f32 v38, v48, v88, v38
	v_mul_f32_e32 v48, v155, v115
	v_fma_f32 v39, v48, v89, v39
	v_mul_f32_e32 v48, v155, v116
	v_fma_f32 v40, v48, v90, v40
	v_mul_f32_e32 v48, v155, v117
	v_fmac_f32_e32 v41, v48, v91
	v_cvt_pk_bf16_f32 v94, v38, v39
	v_cvt_pk_bf16_f32 v95, v40, v41
	ds_read_b128 v[88:91], v81 offset:7168
	v_mul_f32_e32 v48, v155, v118
	global_store_dwordx2 v[92:93], v[94:95], off offset:3072
	s_waitcnt lgkmcnt(0)
	v_fma_f32 v42, v48, v88, v42
	v_mul_f32_e32 v48, v155, v119
	v_fma_f32 v43, v48, v89, v43
	v_mul_f32_e32 v48, v155, v120
	v_fma_f32 v44, v48, v90, v44
	v_mul_f32_e32 v48, v155, v121
	v_fmac_f32_e32 v45, v48, v91
	v_cvt_pk_bf16_f32 v88, v42, v43
	v_cvt_pk_bf16_f32 v89, v44, v45
	global_store_dwordx2 v[92:93], v[88:89], off offset:3584
	ds_read_b128 v[88:91], v81 offset:8192
	v_mul_f32_e32 v48, v155, v122
	v_mul_f32_e32 v59, v155, v123
	v_mul_f32_e32 v60, v155, v124
	v_add_co_u32_e32 v92, vcc, s47, v92
	s_waitcnt lgkmcnt(0)
	v_fma_f32 v34, v48, v88, v34
	v_mul_f32_e32 v48, v155, v125
	v_fma_f32 v35, v59, v89, v35
	v_fma_f32 v36, v60, v90, v36
	v_fmac_f32_e32 v37, v48, v91
	v_cvt_pk_bf16_f32 v94, v34, v35
	v_cvt_pk_bf16_f32 v95, v36, v37
	ds_read_b128 v[88:91], v81 offset:9216
	v_mul_f32_e32 v48, v155, v126
	v_addc_co_u32_e32 v93, vcc, 0, v93, vcc
	global_store_dwordx2 v[92:93], v[94:95], off
	s_waitcnt lgkmcnt(0)
	v_fma_f32 v48, v48, v88, v30
	v_mul_f32_e32 v30, v155, v127
	v_fma_f32 v31, v30, v89, v31
	v_mul_f32_e32 v30, v155, v128
	v_fma_f32 v30, v30, v90, v32
	v_mul_f32_e32 v32, v155, v129
	v_fmac_f32_e32 v33, v32, v91
	v_cvt_pk_bf16_f32 v94, v48, v31
	v_cvt_pk_bf16_f32 v95, v30, v33
	ds_read_b128 v[88:91], v81 offset:10240
	v_mul_f32_e32 v32, v155, v130
	global_store_dwordx2 v[92:93], v[94:95], off offset:512
	s_waitcnt lgkmcnt(0)
	v_fma_f32 v26, v32, v88, v26
	v_mul_f32_e32 v32, v155, v131
	v_fma_f32 v27, v32, v89, v27
	v_mul_f32_e32 v32, v155, v132
	v_fma_f32 v28, v32, v90, v28
	v_mul_f32_e32 v32, v155, v133
	v_fmac_f32_e32 v29, v32, v91
	v_cvt_pk_bf16_f32 v94, v26, v27
	v_cvt_pk_bf16_f32 v95, v28, v29
	ds_read_b128 v[88:91], v81 offset:11264
	v_mul_f32_e32 v32, v155, v134
	global_store_dwordx2 v[92:93], v[94:95], off offset:1024
	s_waitcnt lgkmcnt(0)
	v_fma_f32 v22, v32, v88, v22
	v_mul_f32_e32 v32, v155, v135
	v_fma_f32 v23, v32, v89, v23
	v_mul_f32_e32 v32, v155, v136
	v_fma_f32 v24, v32, v90, v24
	v_mul_f32_e32 v32, v155, v137
	v_fmac_f32_e32 v25, v32, v91
	v_cvt_pk_bf16_f32 v88, v22, v23
	v_cvt_pk_bf16_f32 v89, v24, v25
	global_store_dwordx2 v[92:93], v[88:89], off offset:1536
	ds_read_b128 v[88:91], v81 offset:12288
	v_mul_f32_e32 v32, v155, v138
	v_mul_f32_e32 v59, v155, v139
	v_mul_f32_e32 v60, v155, v140
	s_waitcnt lgkmcnt(0)
	v_fma_f32 v18, v32, v88, v18
	v_mul_f32_e32 v32, v155, v141
	v_fma_f32 v19, v59, v89, v19
	v_fma_f32 v20, v60, v90, v20
	v_fmac_f32_e32 v21, v32, v91
	v_cvt_pk_bf16_f32 v94, v18, v19
	v_cvt_pk_bf16_f32 v95, v20, v21
	ds_read_b128 v[88:91], v81 offset:13312
	v_mul_f32_e32 v32, v155, v142
	global_store_dwordx2 v[92:93], v[94:95], off offset:2048
	s_waitcnt lgkmcnt(0)
	v_fma_f32 v32, v32, v88, v14
	v_mul_f32_e32 v14, v155, v143
	v_fma_f32 v15, v14, v89, v15
	v_mul_f32_e32 v14, v155, v144
	v_fma_f32 v14, v14, v90, v16
	v_mul_f32_e32 v16, v155, v145
	v_fmac_f32_e32 v17, v16, v91
	v_cvt_pk_bf16_f32 v94, v32, v15
	v_cvt_pk_bf16_f32 v95, v14, v17
	ds_read_b128 v[88:91], v81 offset:14336
	v_mul_f32_e32 v16, v155, v147
	global_store_dwordx2 v[92:93], v[94:95], off offset:2560
	s_waitcnt lgkmcnt(0)
	v_fma_f32 v10, v16, v88, v10
	v_mul_f32_e32 v16, v155, v148
	v_fma_f32 v11, v16, v89, v11
	v_mul_f32_e32 v16, v155, v149
	v_fma_f32 v12, v16, v90, v12
	v_mul_f32_e32 v16, v155, v150
	v_fmac_f32_e32 v13, v16, v91
	v_cvt_pk_bf16_f32 v94, v10, v11
	v_cvt_pk_bf16_f32 v95, v12, v13
	ds_read_b128 v[88:91], v81 offset:15360
	v_mul_f32_e32 v16, v155, v151
	global_store_dwordx2 v[92:93], v[94:95], off offset:3072
	s_waitcnt vmcnt(15) lgkmcnt(0)
	v_fma_f32 v6, v16, v88, v6
	v_mul_f32_e32 v16, v155, v152
	v_fma_f32 v7, v16, v89, v7
	v_mul_f32_e32 v16, v155, v153
	v_fma_f32 v8, v16, v90, v8
	v_mul_f32_e32 v16, v155, v154
	v_fmac_f32_e32 v9, v16, v91
	v_cvt_pk_bf16_f32 v88, v6, v7
	v_cvt_pk_bf16_f32 v89, v8, v9
	global_store_dwordx2 v[92:93], v[88:89], off offset:3584
	v_mul_f32_e32 v16, v3, v3
	v_mul_f32_e32 v59, v5, v5
	v_fmac_f32_e32 v16, v2, v2
	v_fmac_f32_e32 v59, v4, v4
	v_add_f32_e32 v16, v16, v59
	v_mul_f32_e32 v59, v63, v63
	v_mul_f32_e32 v60, v65, v65
	v_fmac_f32_e32 v59, v84, v84
	v_fmac_f32_e32 v60, v62, v62
	v_add_f32_e32 v59, v59, v60
	v_add_f32_e32 v16, v16, v59
	v_mul_f32_e32 v59, v55, v55
	v_mul_f32_e32 v60, v57, v57
	v_fmac_f32_e32 v59, v54, v54
	v_fmac_f32_e32 v60, v56, v56
	v_add_f32_e32 v59, v59, v60
	v_add_f32_e32 v16, v16, v59
	v_mul_f32_e32 v59, v85, v85
	v_mul_f32_e32 v60, v53, v53
	v_fmac_f32_e32 v59, v64, v64
	v_fmac_f32_e32 v60, v86, v86
	v_add_f32_e32 v59, v59, v60
	v_add_f32_e32 v16, v16, v59
	v_mul_f32_e32 v59, v51, v51
	v_mul_f32_e32 v60, v61, v61
	v_fmac_f32_e32 v59, v50, v50
	v_fmac_f32_e32 v60, v52, v52
	v_add_f32_e32 v59, v59, v60
	v_add_f32_e32 v16, v16, v59
	v_mul_f32_e32 v59, v47, v47
	v_mul_f32_e32 v60, v49, v49
	v_fmac_f32_e32 v59, v58, v58
	v_fmac_f32_e32 v60, v46, v46
	v_add_f32_e32 v59, v59, v60
	v_add_f32_e32 v16, v16, v59
	v_mul_f32_e32 v59, v39, v39
	v_mul_f32_e32 v60, v41, v41
	v_fmac_f32_e32 v59, v38, v38
	v_fmac_f32_e32 v60, v40, v40
	v_add_f32_e32 v59, v59, v60
	v_add_f32_e32 v16, v16, v59
	v_mul_f32_e32 v59, v43, v43
	v_mul_f32_e32 v60, v45, v45
	v_fmac_f32_e32 v59, v42, v42
	v_fmac_f32_e32 v60, v44, v44
	v_add_f32_e32 v59, v59, v60
	v_add_f32_e32 v16, v16, v59
	v_mul_f32_e32 v59, v35, v35
	v_mul_f32_e32 v60, v37, v37
	v_fmac_f32_e32 v59, v34, v34
	v_fmac_f32_e32 v60, v36, v36
	v_add_f32_e32 v59, v59, v60
	v_add_f32_e32 v16, v16, v59
	v_mul_f32_e32 v59, v31, v31
	v_mul_f32_e32 v60, v33, v33
	v_fmac_f32_e32 v59, v48, v48
	v_fmac_f32_e32 v60, v30, v30
	v_add_f32_e32 v59, v59, v60
	v_add_f32_e32 v16, v16, v59
	v_mul_f32_e32 v59, v27, v27
	v_mul_f32_e32 v60, v29, v29
	v_fmac_f32_e32 v59, v26, v26
	v_fmac_f32_e32 v60, v28, v28
	v_add_f32_e32 v59, v59, v60
	v_add_f32_e32 v16, v16, v59
	v_mul_f32_e32 v59, v23, v23
	v_mul_f32_e32 v60, v25, v25
	v_fmac_f32_e32 v59, v22, v22
	v_fmac_f32_e32 v60, v24, v24
	v_add_f32_e32 v59, v59, v60
	v_add_f32_e32 v16, v16, v59
	v_mul_f32_e32 v59, v19, v19
	v_mul_f32_e32 v60, v21, v21
	v_fmac_f32_e32 v59, v18, v18
	v_fmac_f32_e32 v60, v20, v20
	v_add_f32_e32 v59, v59, v60
	v_add_f32_e32 v16, v16, v59
	v_mul_f32_e32 v59, v15, v15
	v_mul_f32_e32 v60, v17, v17
	v_fmac_f32_e32 v59, v32, v32
	v_fmac_f32_e32 v60, v14, v14
	v_add_f32_e32 v59, v59, v60
	v_add_f32_e32 v16, v16, v59
	v_mul_f32_e32 v59, v11, v11
	v_mul_f32_e32 v60, v13, v13
	v_fmac_f32_e32 v59, v10, v10
	v_fmac_f32_e32 v60, v12, v12
	v_add_f32_e32 v59, v59, v60
	v_add_f32_e32 v16, v16, v59
	v_mul_f32_e32 v59, v7, v7
	v_mul_f32_e32 v60, v9, v9
	v_fmac_f32_e32 v59, v6, v6
	v_fmac_f32_e32 v60, v8, v8
	v_add_f32_e32 v59, v59, v60
	v_add_f32_e32 v16, v16, v59
	ds_bpermute_b32 v59, v1, v16
	s_waitcnt lgkmcnt(0)
	v_add_f32_e32 v16, v16, v59
	ds_bpermute_b32 v59, v76, v16
	s_waitcnt lgkmcnt(0)
	v_add_f32_e32 v16, v16, v59
	ds_bpermute_b32 v59, v77, v16
	s_waitcnt lgkmcnt(0)
	v_add_f32_e32 v16, v16, v59
	ds_bpermute_b32 v59, v78, v16
	s_waitcnt lgkmcnt(0)
	v_add_f32_e32 v16, v16, v59
	ds_bpermute_b32 v59, v79, v16
	s_waitcnt lgkmcnt(0)
	v_add_f32_e32 v16, v16, v59
	ds_bpermute_b32 v59, v80, v16
	s_waitcnt lgkmcnt(0)
	v_add_f32_e32 v16, v16, v59
	v_fmamk_f32 v16, v16, 0x39800000, v66
	v_mul_f32_e32 v59, 0x4f800000, v16
	v_cmp_gt_f32_e32 vcc, s50, v16
	s_nop 1
	v_cndmask_b32_e32 v16, v16, v59, vcc
	v_sqrt_f32_e32 v59, v16
	s_nop 0
	v_add_u32_e32 v60, -1, v59
	v_fma_f32 v87, -v60, v59, v16
	v_cmp_ge_f32_e64 s[8:9], 0, v87
	v_add_u32_e32 v87, 1, v59
	s_nop 0
	v_cndmask_b32_e64 v60, v59, v60, s[8:9]
	v_fma_f32 v59, -v87, v59, v16
	v_cmp_lt_f32_e64 s[8:9], 0, v59
	s_nop 1
	v_cndmask_b32_e64 v59, v60, v87, s[8:9]
	v_mul_f32_e32 v60, 0x37800000, v59
	v_cndmask_b32_e32 v59, v59, v60, vcc
	v_cmp_class_f32_e32 vcc, v16, v82
	s_nop 1
	v_cndmask_b32_e32 v16, v59, v16, vcc
	v_div_scale_f32 v59, s[0:1], v16, v16, 1.0
	v_rcp_f32_e32 v60, v59
	s_nop 0
	v_fma_f32 v87, -v59, v60, 1.0
	v_fmac_f32_e32 v60, v87, v60
	v_div_scale_f32 v87, vcc, 1.0, v16, 1.0
	v_mul_f32_e32 v88, v87, v60
	v_fma_f32 v89, -v59, v88, v87
	v_fmac_f32_e32 v88, v89, v60
	v_fma_f32 v59, -v59, v88, v87
	v_div_fmas_f32 v59, v59, v60, v88
	v_div_fixup_f32 v87, v59, v16, 1.0
	s_and_saveexec_b64 s[0:1], s[6:7]
	s_cbranch_execz .LBB0_483
	s_lshl_b64 s[8:9], s[38:39], 2
	s_add_u32 s8, s10, s8
	s_addc_u32 s9, s11, s9
	global_store_dword v67, v87, s[8:9]

.LBB0_1343:
	s_or_b64 exec, exec, s[0:1]
	s_ashr_i32 s25, s24, 31
	s_lshl_b64 s[0:1], s[24:25], 13
	v_lshl_add_u64 v[12:13], v[6:7], 0, s[0:1]
	global_load_dwordx2 v[38:39], v[12:13], off nt
	global_load_dwordx2 v[40:41], v[12:13], off offset:512 nt
	global_load_dwordx2 v[42:43], v[12:13], off offset:1024 nt
	global_load_dwordx2 v[44:45], v[12:13], off offset:1536 nt
	global_load_dwordx2 v[46:47], v[12:13], off offset:2048 nt
	global_load_dwordx2 v[68:69], v[12:13], off offset:2560 nt
	global_load_dwordx2 v[70:71], v[12:13], off offset:3072 nt
	v_lshl_add_u64 v[14:15], v[4:5], 0, s[0:1]
	global_load_dwordx2 v[22:23], v[12:13], off offset:3584 nt
	global_load_dwordx2 v[72:73], v[14:15], off
	global_load_dwordx2 v[74:75], v[14:15], off offset:512
	global_load_dwordx2 v[76:77], v[14:15], off offset:1024
	global_load_dwordx2 v[78:79], v[14:15], off offset:1536
	global_load_dwordx2 v[80:81], v[14:15], off offset:2048
	global_load_dwordx2 v[82:83], v[14:15], off offset:2560
	global_load_dwordx2 v[84:85], v[14:15], off offset:3072
	global_load_dwordx2 v[86:87], v[14:15], off offset:3584
	v_add_co_u32_e64 v12, s[8:9], s45, v12
	v_add_co_u32_e32 v48, vcc, 0x1000, v14
	s_nop 0
	v_addc_co_u32_e64 v13, s[8:9], 0, v13, s[8:9]
	v_addc_co_u32_e32 v49, vcc, 0, v15, vcc
	global_load_dwordx2 v[28:29], v[12:13], off nt
	global_load_dwordx2 v[26:27], v[12:13], off offset:512 nt
	global_load_dwordx2 v[24:25], v[12:13], off offset:1024 nt
	global_load_dwordx2 v[20:21], v[12:13], off offset:1536 nt
	global_load_dwordx2 v[18:19], v[12:13], off offset:2048 nt
	global_load_dwordx2 v[16:17], v[12:13], off offset:2560 nt
	global_load_dwordx2 v[14:15], v[12:13], off offset:3072 nt
	s_nop 0
	global_load_dwordx2 v[12:13], v[12:13], off offset:3584 nt
	s_nop 0
	global_load_dwordx2 v[88:89], v[48:49], off
	global_load_dwordx2 v[90:91], v[48:49], off offset:512
	global_load_dwordx2 v[92:93], v[48:49], off offset:1024
	global_load_dwordx2 v[94:95], v[48:49], off offset:1536
	global_load_dwordx2 v[96:97], v[48:49], off offset:2048
	global_load_dwordx2 v[98:99], v[48:49], off offset:2560
	global_load_dwordx2 v[100:101], v[48:49], off offset:3072
	global_load_dwordx2 v[102:103], v[48:49], off offset:3584
	s_waitcnt vmcnt(31)
	v_readfirstlane_b32 s98, v223
	s_nop 1
	v_mov_b32_e32 v37, s98
	v_lshlrev_b32_e32 v66, 16, v38
	s_waitcnt vmcnt(23)
	v_and_b32_e32 v105, 0xffff0000, v72
	v_and_b32_e32 v107, 0xffff0000, v73
	v_lshlrev_b32_e32 v52, 16, v45
	v_and_b32_e32 v51, 0xffff0000, v45
	v_lshlrev_b32_e32 v48, 16, v46
	v_and_b32_e32 v49, 0xffff0000, v46
	v_lshlrev_b32_e32 v46, 16, v68
	v_and_b32_e32 v45, 0xffff0000, v68
	v_lshlrev_b32_e32 v104, 16, v72
	v_lshlrev_b32_e32 v106, 16, v73
	v_mul_f32_e32 v67, v105, v105
	v_mul_f32_e32 v68, v107, v107
	s_waitcnt vmcnt(22)
	v_and_b32_e32 v109, 0xffff0000, v74
	v_and_b32_e32 v111, 0xffff0000, v75
	v_fmac_f32_e32 v67, v104, v104
	v_fmac_f32_e32 v68, v106, v106
	v_lshlrev_b32_e32 v56, 16, v43
	v_and_b32_e32 v55, 0xffff0000, v43
	v_lshlrev_b32_e32 v54, 16, v44
	v_and_b32_e32 v53, 0xffff0000, v44
	v_lshlrev_b32_e32 v44, 16, v69
	v_and_b32_e32 v43, 0xffff0000, v69
	v_lshlrev_b32_e32 v108, 16, v74
	v_lshlrev_b32_e32 v110, 16, v75
	v_add_f32_e32 v67, v67, v68
	v_mul_f32_e32 v68, v109, v109
	v_mul_f32_e32 v69, v111, v111
	v_fmac_f32_e32 v68, v108, v108
	v_fmac_f32_e32 v69, v110, v110
	v_add_f32_e32 v68, v68, v69
	s_waitcnt vmcnt(21)
	v_and_b32_e32 v113, 0xffff0000, v76
	v_and_b32_e32 v115, 0xffff0000, v77
	v_add_f32_e32 v67, v67, v68
	v_lshlrev_b32_e32 v112, 16, v76
	v_lshlrev_b32_e32 v114, 16, v77
	v_mul_f32_e32 v68, v113, v113
	v_mul_f32_e32 v69, v115, v115
	v_fmac_f32_e32 v68, v112, v112
	v_fmac_f32_e32 v69, v114, v114
	v_add_f32_e32 v68, v68, v69
	s_waitcnt vmcnt(20)
	v_and_b32_e32 v117, 0xffff0000, v78
	v_and_b32_e32 v119, 0xffff0000, v79
	v_add_f32_e32 v67, v67, v68
	v_lshlrev_b32_e32 v116, 16, v78
	v_lshlrev_b32_e32 v118, 16, v79
	v_mul_f32_e32 v68, v117, v117
	v_mul_f32_e32 v69, v119, v119
	v_fmac_f32_e32 v68, v116, v116
	v_fmac_f32_e32 v69, v118, v118
	v_add_f32_e32 v68, v68, v69
	s_waitcnt vmcnt(19)
	v_and_b32_e32 v121, 0xffff0000, v80
	v_and_b32_e32 v123, 0xffff0000, v81
	v_add_f32_e32 v67, v67, v68
	v_lshlrev_b32_e32 v120, 16, v80
	v_lshlrev_b32_e32 v122, 16, v81
	v_mul_f32_e32 v68, v121, v121
	v_mul_f32_e32 v69, v123, v123
	v_fmac_f32_e32 v68, v120, v120
	v_fmac_f32_e32 v69, v122, v122
	v_add_f32_e32 v68, v68, v69
	s_waitcnt vmcnt(18)
	v_and_b32_e32 v125, 0xffff0000, v82
	v_and_b32_e32 v127, 0xffff0000, v83
	v_add_f32_e32 v67, v67, v68
	v_lshlrev_b32_e32 v124, 16, v82
	v_lshlrev_b32_e32 v126, 16, v83
	v_mul_f32_e32 v68, v125, v125
	v_mul_f32_e32 v69, v127, v127
	v_fmac_f32_e32 v68, v124, v124
	v_fmac_f32_e32 v69, v126, v126
	v_add_f32_e32 v68, v68, v69
	s_waitcnt vmcnt(17)
	v_and_b32_e32 v129, 0xffff0000, v84
	v_and_b32_e32 v131, 0xffff0000, v85
	v_add_f32_e32 v67, v67, v68
	v_lshlrev_b32_e32 v128, 16, v84
	v_lshlrev_b32_e32 v130, 16, v85
	v_mul_f32_e32 v68, v129, v129
	v_mul_f32_e32 v69, v131, v131
	v_fmac_f32_e32 v68, v128, v128
	v_fmac_f32_e32 v69, v130, v130
	v_add_f32_e32 v68, v68, v69
	s_waitcnt vmcnt(16)
	v_and_b32_e32 v133, 0xffff0000, v86
	v_and_b32_e32 v135, 0xffff0000, v87
	v_add_f32_e32 v67, v67, v68
	v_lshlrev_b32_e32 v132, 16, v86
	v_lshlrev_b32_e32 v134, 16, v87
	v_mul_f32_e32 v68, v133, v133
	v_mul_f32_e32 v69, v135, v135
	v_fmac_f32_e32 v68, v132, v132
	v_fmac_f32_e32 v69, v134, v134
	v_add_f32_e32 v68, v68, v69
	s_waitcnt vmcnt(7)
	v_and_b32_e32 v137, 0xffff0000, v88
	v_and_b32_e32 v139, 0xffff0000, v89
	v_add_f32_e32 v67, v67, v68
	v_lshlrev_b32_e32 v136, 16, v88
	v_lshlrev_b32_e32 v138, 16, v89
	v_mul_f32_e32 v68, v137, v137
	v_mul_f32_e32 v69, v139, v139
	v_fmac_f32_e32 v68, v136, v136
	v_fmac_f32_e32 v69, v138, v138
	v_add_f32_e32 v68, v68, v69
	s_waitcnt vmcnt(6)
	v_and_b32_e32 v141, 0xffff0000, v90
	v_and_b32_e32 v143, 0xffff0000, v91
	v_add_f32_e32 v67, v67, v68
	v_lshlrev_b32_e32 v140, 16, v90
	v_lshlrev_b32_e32 v142, 16, v91
	v_mul_f32_e32 v68, v141, v141
	v_mul_f32_e32 v69, v143, v143
	v_fmac_f32_e32 v68, v140, v140
	v_fmac_f32_e32 v69, v142, v142
	v_add_f32_e32 v68, v68, v69
	s_waitcnt vmcnt(5)
	v_lshlrev_b32_e32 v144, 16, v92
	v_and_b32_e32 v92, 0xffff0000, v92
	v_lshlrev_b32_e32 v145, 16, v93
	v_and_b32_e32 v93, 0xffff0000, v93
	v_add_f32_e32 v67, v67, v68
	v_mul_f32_e32 v68, v92, v92
	v_mul_f32_e32 v69, v93, v93
	v_fmac_f32_e32 v68, v144, v144
	v_fmac_f32_e32 v69, v145, v145
	v_add_f32_e32 v68, v68, v69
	s_waitcnt vmcnt(4)
	v_lshlrev_b32_e32 v147, 16, v94
	v_and_b32_e32 v94, 0xffff0000, v94
	v_lshlrev_b32_e32 v148, 16, v95
	v_and_b32_e32 v95, 0xffff0000, v95
	v_add_f32_e32 v67, v67, v68
	v_mul_f32_e32 v68, v94, v94
	v_mul_f32_e32 v69, v95, v95
	v_fmac_f32_e32 v68, v147, v147
	v_fmac_f32_e32 v69, v148, v148
	v_add_f32_e32 v68, v68, v69
	s_waitcnt vmcnt(3)
	v_lshlrev_b32_e32 v149, 16, v96
	v_and_b32_e32 v96, 0xffff0000, v96
	v_lshlrev_b32_e32 v150, 16, v97
	v_and_b32_e32 v97, 0xffff0000, v97
	v_add_f32_e32 v67, v67, v68
	v_mul_f32_e32 v68, v96, v96
	v_mul_f32_e32 v69, v97, v97
	v_fmac_f32_e32 v68, v149, v149
	v_fmac_f32_e32 v69, v150, v150
	v_add_f32_e32 v68, v68, v69
	s_waitcnt vmcnt(2)
	v_lshlrev_b32_e32 v151, 16, v98
	v_and_b32_e32 v98, 0xffff0000, v98
	v_lshlrev_b32_e32 v152, 16, v99
	v_and_b32_e32 v99, 0xffff0000, v99
	v_add_f32_e32 v67, v67, v68
	v_mul_f32_e32 v68, v98, v98
	v_mul_f32_e32 v69, v99, v99
	v_fmac_f32_e32 v68, v151, v151
	v_fmac_f32_e32 v69, v152, v152
	v_add_f32_e32 v68, v68, v69
	s_waitcnt vmcnt(1)
	v_lshlrev_b32_e32 v153, 16, v100
	v_and_b32_e32 v100, 0xffff0000, v100
	v_lshlrev_b32_e32 v154, 16, v101
	v_and_b32_e32 v101, 0xffff0000, v101
	v_add_f32_e32 v67, v67, v68
	v_mul_f32_e32 v68, v100, v100
	v_mul_f32_e32 v69, v101, v101
	v_fmac_f32_e32 v68, v153, v153
	v_fmac_f32_e32 v69, v154, v154
	v_add_f32_e32 v68, v68, v69
	s_waitcnt vmcnt(0)
	v_lshlrev_b32_e32 v155, 16, v102
	v_and_b32_e32 v102, 0xffff0000, v102
	v_lshlrev_b32_e32 v156, 16, v103
	v_and_b32_e32 v103, 0xffff0000, v103
	v_add_f32_e32 v67, v67, v68
	v_mul_f32_e32 v68, v102, v102
	v_mul_f32_e32 v69, v103, v103
	v_fmac_f32_e32 v68, v155, v155
	v_fmac_f32_e32 v69, v156, v156
	v_add_f32_e32 v68, v68, v69
	v_add_f32_e32 v67, v67, v68
	ds_bpermute_b32 v68, v1, v67
	v_and_b32_e32 v65, 0xffff0000, v38
	v_lshlrev_b32_e32 v38, 16, v22
	v_and_b32_e32 v81, 0xffff0000, v22
	v_lshlrev_b32_e32 v80, 16, v23
	s_waitcnt lgkmcnt(0)
	v_add_f32_e32 v22, v67, v68
	v_and_b32_e32 v79, 0xffff0000, v23
	ds_bpermute_b32 v23, v30, v22
	v_lshlrev_b32_e32 v73, 16, v28
	v_and_b32_e32 v77, 0xffff0000, v28
	v_lshlrev_b32_e32 v74, 16, v26
	v_and_b32_e32 v76, 0xffff0000, v26
	s_waitcnt lgkmcnt(0)
	v_add_f32_e32 v22, v22, v23
	ds_bpermute_b32 v23, v31, v22
	v_lshlrev_b32_e32 v28, 16, v21
	v_and_b32_e32 v26, 0xffff0000, v21
	v_lshlrev_b32_e32 v60, 16, v41
	v_and_b32_e32 v59, 0xffff0000, v41
	s_waitcnt lgkmcnt(0)
	v_add_f32_e32 v22, v22, v23
	ds_bpermute_b32 v23, v32, v22
	v_lshlrev_b32_e32 v58, 16, v42
	v_and_b32_e32 v57, 0xffff0000, v42
	v_lshlrev_b32_e32 v42, 16, v70
	v_and_b32_e32 v41, 0xffff0000, v70
	s_waitcnt lgkmcnt(0)
	v_add_f32_e32 v22, v22, v23
	ds_bpermute_b32 v23, v33, v22
	v_lshlrev_b32_e32 v68, 16, v24
	v_and_b32_e32 v70, 0xffff0000, v24
	v_lshlrev_b32_e32 v64, 16, v39
	v_and_b32_e32 v63, 0xffff0000, v39
	s_waitcnt lgkmcnt(0)
	v_add_f32_e32 v21, v22, v23
	ds_bpermute_b32 v24, v34, v21
	v_lshlrev_b32_e32 v62, 16, v40
	v_and_b32_e32 v61, 0xffff0000, v40
	v_lshlrev_b32_e32 v40, 16, v71
	v_and_b32_e32 v39, 0xffff0000, v71
	s_waitcnt lgkmcnt(0)
	v_add_f32_e32 v21, v21, v24
	v_fmamk_f32 v21, v21, 0x39800000, v2
	v_mul_f32_e32 v24, 0x4f800000, v21
	v_cmp_gt_f32_e32 vcc, s46, v21
	v_lshlrev_b32_e32 v78, 16, v29
	v_and_b32_e32 v75, 0xffff0000, v29
	v_cndmask_b32_e32 v24, v21, v24, vcc
	v_sqrt_f32_e32 v82, v24
	v_lshlrev_b32_e32 v72, 16, v27
	v_and_b32_e32 v71, 0xffff0000, v27
	v_lshlrev_b32_e32 v69, 16, v25
	v_and_b32_e32 v29, 0xffff0000, v25
	v_lshlrev_b32_e32 v27, 16, v20
	v_and_b32_e32 v67, 0xffff0000, v20
	v_lshlrev_b32_e32 v20, 16, v18
	v_and_b32_e32 v22, 0xffff0000, v18
	v_lshlrev_b32_e32 v18, 16, v16
	v_and_b32_e32 v25, 0xffff0000, v16
	v_lshlrev_b32_e32 v21, 16, v17
	v_and_b32_e32 v16, 0xffff0000, v17
	v_add_u32_e32 v17, -1, v82
	v_fma_f32 v83, -v17, v82, v24
	v_cmp_ge_f32_e64 s[8:9], 0, v83
	v_add_u32_e32 v83, 1, v82
	v_lshlrev_b32_e32 v50, 16, v47
	v_cndmask_b32_e64 v17, v82, v17, s[8:9]
	v_fma_f32 v82, -v83, v82, v24
	v_cmp_lt_f32_e64 s[8:9], 0, v82
	v_and_b32_e32 v47, 0xffff0000, v47
	v_lshlrev_b32_e32 v23, 16, v19
	v_cndmask_b32_e64 v17, v17, v83, s[8:9]
	v_mul_f32_e32 v82, 0x37800000, v17
	v_cndmask_b32_e32 v17, v17, v82, vcc
	v_cmp_class_f32_e32 vcc, v24, v36
	v_and_b32_e32 v19, 0xffff0000, v19
	s_nop 0
	v_cndmask_b32_e32 v86, v17, v24, vcc
	v_div_scale_f32 v82, s[8:9], v86, v86, 1.0
	v_rcp_f32_e32 v87, v82
	v_lshlrev_b32_e32 v24, 16, v14
	v_and_b32_e32 v17, 0xffff0000, v14
	v_lshlrev_b32_e32 v14, 16, v15
	v_fma_f32 v83, -v82, v87, 1.0
	v_fmac_f32_e32 v87, v83, v87
	v_div_scale_f32 v83, vcc, 1.0, v86, 1.0
	v_mul_f32_e32 v88, v83, v87
	v_fma_f32 v84, -v82, v88, v83
	v_fmac_f32_e32 v88, v84, v87
	v_fma_f32 v89, -v82, v88, v83
	ds_read_b128 v[82:85], v35
	v_div_fmas_f32 v87, v89, v87, v88
	v_div_fixup_f32 v157, v87, v86, 1.0
	v_mul_f32_e32 v86, v157, v104
	v_lshl_add_u64 v[88:89], v[8:9], 0, s[0:1]
	s_waitcnt lgkmcnt(0)
	v_fmac_f32_e32 v66, v82, v86
	v_mul_f32_e32 v82, v157, v105
	v_fmac_f32_e32 v65, v83, v82
	v_mul_f32_e32 v82, v157, v106
	v_fmac_f32_e32 v64, v84, v82
	v_mul_f32_e32 v82, v157, v107
	v_fmac_f32_e32 v63, v85, v82
	v_cvt_pk_bf16_f32 v86, v66, v65
	v_cvt_pk_bf16_f32 v87, v64, v63
	ds_read_b128 v[82:85], v35 offset:1024
	global_store_dwordx2 v[88:89], v[86:87], off
	v_mul_f32_e32 v86, v157, v108
	v_and_b32_e32 v15, 0xffff0000, v15
	s_waitcnt lgkmcnt(0)
	v_fmac_f32_e32 v62, v82, v86
	v_mul_f32_e32 v82, v157, v109
	v_fmac_f32_e32 v61, v83, v82
	v_mul_f32_e32 v82, v157, v110
	v_fmac_f32_e32 v60, v84, v82
	v_mul_f32_e32 v82, v157, v111
	v_fmac_f32_e32 v59, v85, v82
	v_cvt_pk_bf16_f32 v90, v62, v61
	v_cvt_pk_bf16_f32 v91, v60, v59
	ds_read_b128 v[84:87], v35 offset:2048
	v_mul_f32_e32 v83, v157, v112
	global_store_dwordx2 v[88:89], v[90:91], off offset:512
	v_lshlrev_b32_e32 v82, 16, v12
	v_and_b32_e32 v12, 0xffff0000, v12
	s_waitcnt lgkmcnt(0)
	v_fmac_f32_e32 v58, v83, v84
	v_mul_f32_e32 v83, v157, v113
	v_fmac_f32_e32 v57, v83, v85
	v_mul_f32_e32 v83, v157, v114
	v_fmac_f32_e32 v56, v83, v86
	v_mul_f32_e32 v83, v157, v115
	v_fmac_f32_e32 v55, v83, v87
	v_cvt_pk_bf16_f32 v90, v58, v57
	v_cvt_pk_bf16_f32 v91, v56, v55
	ds_read_b128 v[84:87], v35 offset:3072
	global_store_dwordx2 v[88:89], v[90:91], off offset:1024
	v_mul_f32_e32 v90, v157, v116
	v_lshlrev_b32_e32 v83, 16, v13
	v_and_b32_e32 v13, 0xffff0000, v13
	s_waitcnt lgkmcnt(0)
	v_fmac_f32_e32 v54, v90, v84
	v_mul_f32_e32 v84, v157, v117
	v_fmac_f32_e32 v53, v84, v85
	v_mul_f32_e32 v84, v157, v118
	v_fmac_f32_e32 v52, v84, v86
	v_mul_f32_e32 v84, v157, v119
	v_fmac_f32_e32 v51, v84, v87
	v_cvt_pk_bf16_f32 v84, v54, v53
	v_cvt_pk_bf16_f32 v85, v52, v51
	global_store_dwordx2 v[88:89], v[84:85], off offset:1536
	ds_read_b128 v[84:87], v35 offset:4096
	v_mul_f32_e32 v90, v157, v120
	v_mul_f32_e32 v91, v157, v121
	v_mul_f32_e32 v104, v157, v122
	s_waitcnt lgkmcnt(0)
	v_fmac_f32_e32 v48, v90, v84
	v_mul_f32_e32 v84, v157, v123
	v_fmac_f32_e32 v49, v91, v85
	v_fmac_f32_e32 v50, v104, v86
	v_fmac_f32_e32 v47, v84, v87
	v_cvt_pk_bf16_f32 v90, v48, v49
	v_cvt_pk_bf16_f32 v91, v50, v47
	ds_read_b128 v[84:87], v35 offset:5120
	global_store_dwordx2 v[88:89], v[90:91], off offset:2048
	v_mul_f32_e32 v90, v157, v124
	s_waitcnt lgkmcnt(0)
	v_fmac_f32_e32 v46, v90, v84
	v_mul_f32_e32 v84, v157, v125
	v_fmac_f32_e32 v45, v84, v85
	v_mul_f32_e32 v84, v157, v126
	v_fmac_f32_e32 v44, v84, v86
	v_mul_f32_e32 v84, v157, v127
	v_fmac_f32_e32 v43, v84, v87
	v_cvt_pk_bf16_f32 v90, v46, v45
	v_cvt_pk_bf16_f32 v91, v44, v43
	ds_read_b128 v[84:87], v35 offset:6144
	global_store_dwordx2 v[88:89], v[90:91], off offset:2560
	v_mul_f32_e32 v90, v157, v128
	s_waitcnt lgkmcnt(0)
	v_fmac_f32_e32 v42, v90, v84
	v_mul_f32_e32 v84, v157, v129
	v_fmac_f32_e32 v41, v84, v85
	v_mul_f32_e32 v84, v157, v130
	v_fmac_f32_e32 v40, v84, v86
	v_mul_f32_e32 v84, v157, v131
	v_fmac_f32_e32 v39, v84, v87
	v_cvt_pk_bf16_f32 v90, v42, v41
	v_cvt_pk_bf16_f32 v91, v40, v39
	ds_read_b128 v[84:87], v35 offset:7168
	global_store_dwordx2 v[88:89], v[90:91], off offset:3072
	v_mul_f32_e32 v90, v157, v132
	s_waitcnt lgkmcnt(0)
	v_fmac_f32_e32 v38, v90, v84
	v_mul_f32_e32 v84, v157, v133
	v_fmac_f32_e32 v81, v84, v85
	v_mul_f32_e32 v84, v157, v134
	v_fmac_f32_e32 v80, v84, v86
	v_mul_f32_e32 v84, v157, v135
	v_fmac_f32_e32 v79, v84, v87
	v_cvt_pk_bf16_f32 v84, v38, v81
	v_cvt_pk_bf16_f32 v85, v80, v79
	global_store_dwordx2 v[88:89], v[84:85], off offset:3584
	ds_read_b128 v[84:87], v35 offset:8192
	v_mul_f32_e32 v90, v157, v136
	v_mul_f32_e32 v91, v157, v137
	v_mul_f32_e32 v104, v157, v138
	v_add_co_u32_e32 v88, vcc, s45, v88
	s_waitcnt lgkmcnt(0)
	v_fmac_f32_e32 v73, v90, v84
	v_mul_f32_e32 v84, v157, v139
	v_fmac_f32_e32 v77, v91, v85
	v_fmac_f32_e32 v78, v104, v86
	v_fmac_f32_e32 v75, v84, v87
	v_cvt_pk_bf16_f32 v90, v73, v77
	v_cvt_pk_bf16_f32 v91, v78, v75
	ds_read_b128 v[84:87], v35 offset:9216
	v_addc_co_u32_e32 v89, vcc, 0, v89, vcc
	global_store_dwordx2 v[88:89], v[90:91], off
	v_mul_f32_e32 v90, v157, v140
	s_waitcnt lgkmcnt(0)
	v_fmac_f32_e32 v74, v90, v84
	v_mul_f32_e32 v84, v157, v141
	v_fmac_f32_e32 v76, v84, v85
	v_mul_f32_e32 v84, v157, v142
	v_fmac_f32_e32 v72, v84, v86
	v_mul_f32_e32 v84, v157, v143
	v_fmac_f32_e32 v71, v84, v87
	v_cvt_pk_bf16_f32 v90, v74, v76
	v_cvt_pk_bf16_f32 v91, v72, v71
	ds_read_b128 v[84:87], v35 offset:10240
	global_store_dwordx2 v[88:89], v[90:91], off offset:512
	v_mul_f32_e32 v90, v157, v144
	s_waitcnt lgkmcnt(0)
	v_fmac_f32_e32 v68, v90, v84
	v_mul_f32_e32 v84, v157, v92
	v_fmac_f32_e32 v70, v84, v85
	v_mul_f32_e32 v84, v157, v145
	v_fmac_f32_e32 v69, v84, v86
	v_mul_f32_e32 v84, v157, v93
	v_fmac_f32_e32 v29, v84, v87
	v_cvt_pk_bf16_f32 v90, v68, v70
	v_cvt_pk_bf16_f32 v91, v69, v29
	ds_read_b128 v[84:87], v35 offset:11264
	global_store_dwordx2 v[88:89], v[90:91], off offset:1024
	v_mul_f32_e32 v90, v157, v147
	s_waitcnt lgkmcnt(0)
	v_fmac_f32_e32 v27, v90, v84
	v_mul_f32_e32 v84, v157, v94
	v_fmac_f32_e32 v67, v84, v85
	v_mul_f32_e32 v84, v157, v148
	v_fmac_f32_e32 v28, v84, v86
	v_mul_f32_e32 v84, v157, v95
	v_fmac_f32_e32 v26, v84, v87
	v_cvt_pk_bf16_f32 v84, v27, v67
	v_cvt_pk_bf16_f32 v85, v28, v26
	global_store_dwordx2 v[88:89], v[84:85], off offset:1536
	ds_read_b128 v[84:87], v35 offset:12288
	v_mul_f32_e32 v90, v157, v149
	v_mul_f32_e32 v91, v157, v96
	v_mul_f32_e32 v92, v157, v150
	s_waitcnt lgkmcnt(0)
	v_fmac_f32_e32 v20, v90, v84
	v_mul_f32_e32 v84, v157, v97
	v_fmac_f32_e32 v22, v91, v85
	v_fmac_f32_e32 v23, v92, v86
	v_fmac_f32_e32 v19, v84, v87
	v_cvt_pk_bf16_f32 v90, v20, v22
	v_cvt_pk_bf16_f32 v91, v23, v19
	ds_read_b128 v[84:87], v35 offset:13312
	global_store_dwordx2 v[88:89], v[90:91], off offset:2048
	v_mul_f32_e32 v90, v157, v151
	s_waitcnt lgkmcnt(0)
	v_fmac_f32_e32 v18, v90, v84
	v_mul_f32_e32 v84, v157, v98
	v_fmac_f32_e32 v25, v84, v85
	v_mul_f32_e32 v84, v157, v152
	v_fmac_f32_e32 v21, v84, v86
	v_mul_f32_e32 v84, v157, v99
	v_fmac_f32_e32 v16, v84, v87
	v_cvt_pk_bf16_f32 v90, v18, v25
	v_cvt_pk_bf16_f32 v91, v21, v16
	ds_read_b128 v[84:87], v35 offset:14336
	global_store_dwordx2 v[88:89], v[90:91], off offset:2560
	v_mul_f32_e32 v90, v157, v153
	s_waitcnt lgkmcnt(0)
	v_fmac_f32_e32 v24, v90, v84
	v_mul_f32_e32 v84, v157, v100
	v_fmac_f32_e32 v17, v84, v85
	v_mul_f32_e32 v84, v157, v154
	v_fmac_f32_e32 v14, v84, v86
	v_mul_f32_e32 v84, v157, v101
	v_fmac_f32_e32 v15, v84, v87
	v_cvt_pk_bf16_f32 v90, v24, v17
	v_cvt_pk_bf16_f32 v91, v14, v15
	ds_read_b128 v[84:87], v35 offset:15360
	global_store_dwordx2 v[88:89], v[90:91], off offset:3072
	v_mul_f32_e32 v90, v157, v155
	s_waitcnt lgkmcnt(0)
	v_fmac_f32_e32 v82, v90, v84
	v_mul_f32_e32 v84, v157, v102
	v_fmac_f32_e32 v12, v84, v85
	v_mul_f32_e32 v84, v157, v156
	v_fmac_f32_e32 v83, v84, v86
	v_mul_f32_e32 v84, v157, v103
	v_fmac_f32_e32 v13, v84, v87
	v_cvt_pk_bf16_f32 v84, v82, v12
	v_cvt_pk_bf16_f32 v85, v83, v13
	global_store_dwordx2 v[88:89], v[84:85], off offset:3584
	v_mul_f32_e32 v84, v65, v65
	v_mul_f32_e32 v85, v63, v63
	v_fmac_f32_e32 v84, v66, v66
	v_fmac_f32_e32 v85, v64, v64
	v_add_f32_e32 v84, v84, v85
	v_mul_f32_e32 v85, v61, v61
	v_mul_f32_e32 v86, v59, v59
	v_fmac_f32_e32 v85, v62, v62
	v_fmac_f32_e32 v86, v60, v60
	v_add_f32_e32 v85, v85, v86
	v_add_f32_e32 v84, v84, v85
	v_mul_f32_e32 v85, v57, v57
	v_mul_f32_e32 v86, v55, v55
	v_fmac_f32_e32 v85, v58, v58
	v_fmac_f32_e32 v86, v56, v56
	v_add_f32_e32 v85, v85, v86
	v_add_f32_e32 v84, v84, v85
	v_mul_f32_e32 v85, v53, v53
	v_mul_f32_e32 v86, v51, v51
	v_fmac_f32_e32 v85, v54, v54
	v_fmac_f32_e32 v86, v52, v52
	v_add_f32_e32 v85, v85, v86
	v_add_f32_e32 v84, v84, v85
	v_mul_f32_e32 v85, v49, v49
	v_mul_f32_e32 v86, v47, v47
	v_fmac_f32_e32 v85, v48, v48
	v_fmac_f32_e32 v86, v50, v50
	v_add_f32_e32 v85, v85, v86
	v_add_f32_e32 v84, v84, v85
	v_mul_f32_e32 v85, v45, v45
	v_mul_f32_e32 v86, v43, v43
	v_fmac_f32_e32 v85, v46, v46
	v_fmac_f32_e32 v86, v44, v44
	v_add_f32_e32 v85, v85, v86
	v_add_f32_e32 v84, v84, v85
	v_mul_f32_e32 v85, v41, v41
	v_mul_f32_e32 v86, v39, v39
	v_fmac_f32_e32 v85, v42, v42
	v_fmac_f32_e32 v86, v40, v40
	v_add_f32_e32 v85, v85, v86
	v_add_f32_e32 v84, v84, v85
	v_mul_f32_e32 v85, v81, v81
	v_mul_f32_e32 v86, v79, v79
	v_fmac_f32_e32 v85, v38, v38
	v_fmac_f32_e32 v86, v80, v80
	v_add_f32_e32 v85, v85, v86
	v_add_f32_e32 v84, v84, v85
	v_mul_f32_e32 v85, v77, v77
	v_mul_f32_e32 v86, v75, v75
	v_fmac_f32_e32 v85, v73, v73
	v_fmac_f32_e32 v86, v78, v78
	v_add_f32_e32 v85, v85, v86
	v_add_f32_e32 v84, v84, v85
	v_mul_f32_e32 v85, v76, v76
	v_mul_f32_e32 v86, v71, v71
	v_fmac_f32_e32 v85, v74, v74
	v_fmac_f32_e32 v86, v72, v72
	v_add_f32_e32 v85, v85, v86
	v_add_f32_e32 v84, v84, v85
	v_mul_f32_e32 v85, v70, v70
	v_mul_f32_e32 v86, v29, v29
	v_fmac_f32_e32 v85, v68, v68
	v_fmac_f32_e32 v86, v69, v69
	v_add_f32_e32 v85, v85, v86
	v_add_f32_e32 v84, v84, v85
	v_mul_f32_e32 v85, v67, v67
	v_mul_f32_e32 v86, v26, v26
	v_fmac_f32_e32 v85, v27, v27
	v_fmac_f32_e32 v86, v28, v28
	v_add_f32_e32 v85, v85, v86
	v_add_f32_e32 v84, v84, v85
	v_mul_f32_e32 v85, v22, v22
	v_mul_f32_e32 v86, v19, v19
	v_fmac_f32_e32 v85, v20, v20
	v_fmac_f32_e32 v86, v23, v23
	v_add_f32_e32 v85, v85, v86
	v_add_f32_e32 v84, v84, v85
	v_mul_f32_e32 v85, v25, v25
	v_mul_f32_e32 v86, v16, v16
	v_fmac_f32_e32 v85, v18, v18
	v_fmac_f32_e32 v86, v21, v21
	v_add_f32_e32 v85, v85, v86
	v_add_f32_e32 v84, v84, v85
	v_mul_f32_e32 v85, v17, v17
	v_mul_f32_e32 v86, v15, v15
	v_fmac_f32_e32 v85, v24, v24
	v_fmac_f32_e32 v86, v14, v14
	v_add_f32_e32 v85, v85, v86
	v_add_f32_e32 v84, v84, v85
	v_mul_f32_e32 v85, v12, v12
	v_mul_f32_e32 v86, v13, v13
	v_fmac_f32_e32 v85, v82, v82
	v_fmac_f32_e32 v86, v83, v83
	v_add_f32_e32 v85, v85, v86
	v_add_f32_e32 v84, v84, v85
	ds_bpermute_b32 v85, v1, v84
	s_waitcnt lgkmcnt(0)
	v_add_f32_e32 v84, v84, v85
	ds_bpermute_b32 v85, v30, v84
	s_waitcnt lgkmcnt(0)
	v_add_f32_e32 v84, v84, v85
	ds_bpermute_b32 v85, v31, v84
	s_waitcnt lgkmcnt(0)
	v_add_f32_e32 v84, v84, v85
	ds_bpermute_b32 v85, v32, v84
	s_waitcnt lgkmcnt(0)
	v_add_f32_e32 v84, v84, v85
	ds_bpermute_b32 v85, v33, v84
	s_waitcnt lgkmcnt(0)
	v_add_f32_e32 v84, v84, v85
	ds_bpermute_b32 v85, v34, v84
	s_waitcnt lgkmcnt(0)
	v_add_f32_e32 v84, v84, v85
	v_fmamk_f32 v84, v84, 0x39800000, v2
	v_mul_f32_e32 v85, 0x4f800000, v84
	v_cmp_gt_f32_e32 vcc, s46, v84
	s_nop 1
	v_cndmask_b32_e32 v84, v84, v85, vcc
	v_sqrt_f32_e32 v85, v84
	s_nop 0
	v_add_u32_e32 v86, -1, v85
	v_fma_f32 v87, -v86, v85, v84
	v_cmp_ge_f32_e64 s[8:9], 0, v87
	v_add_u32_e32 v87, 1, v85
	s_nop 0
	v_cndmask_b32_e64 v86, v85, v86, s[8:9]
	v_fma_f32 v85, -v87, v85, v84
	v_cmp_lt_f32_e64 s[8:9], 0, v85
	s_nop 1
	v_cndmask_b32_e64 v85, v86, v87, s[8:9]
	v_mul_f32_e32 v86, 0x37800000, v85
	v_cndmask_b32_e32 v85, v85, v86, vcc
	v_cmp_class_f32_e32 vcc, v84, v36
	s_nop 1
	v_cndmask_b32_e32 v88, v85, v84, vcc
	v_div_scale_f32 v84, s[0:1], v88, v88, 1.0
	v_rcp_f32_e32 v89, v84
	s_nop 0
	v_fma_f32 v85, -v84, v89, 1.0
	v_fmac_f32_e32 v89, v85, v89
	v_div_scale_f32 v85, vcc, 1.0, v88, 1.0
	v_mul_f32_e32 v90, v85, v89
	v_fma_f32 v86, -v84, v90, v85
	v_fmac_f32_e32 v90, v86, v89
	v_fma_f32 v91, -v84, v90, v85
	ds_read_b128 v[84:87], v35 offset:16384
	v_div_fmas_f32 v89, v91, v89, v90
	v_div_fixup_f32 v94, v89, v88, 1.0
	ds_read_b128 v[88:91], v35 offset:17408
	s_waitcnt lgkmcnt(1)
	v_mul_f32_e32 v84, v84, v94
	v_mul_f32_e32 v66, v66, v84
	v_mul_f32_e32 v84, v85, v94
	v_mul_f32_e32 v65, v65, v84
	v_mul_f32_e32 v84, v86, v94
	v_mul_f32_e32 v64, v64, v84
	v_mul_f32_e32 v84, v87, v94
	v_mul_f32_e32 v63, v63, v84
	s_waitcnt lgkmcnt(0)
	v_mul_f32_e32 v84, v88, v94
	v_mul_f32_e32 v62, v62, v84
	v_mul_f32_e32 v84, v89, v94
	v_mul_f32_e32 v61, v61, v84
	ds_read_b128 v[84:87], v35 offset:18432
	v_mul_f32_e32 v88, v90, v94
	v_mul_f32_e32 v60, v60, v88
	v_mul_f32_e32 v88, v91, v94
	v_mul_f32_e32 v59, v59, v88
	ds_read_b128 v[88:91], v35 offset:19456
	s_waitcnt lgkmcnt(1)
	v_mul_f32_e32 v84, v84, v94
	v_mul_f32_e32 v58, v58, v84
	v_mul_f32_e32 v84, v85, v94
	v_mul_f32_e32 v57, v57, v84
	v_mul_f32_e32 v84, v86, v94
	v_mul_f32_e32 v56, v56, v84
	v_mul_f32_e32 v84, v87, v94
	v_mul_f32_e32 v55, v55, v84
	s_waitcnt lgkmcnt(0)
	v_mul_f32_e32 v84, v88, v94
	v_mul_f32_e32 v54, v54, v84
	v_mul_f32_e32 v84, v89, v94
	v_mul_f32_e32 v53, v53, v84
	v_mul_f32_e32 v84, v90, v94
	v_mul_f32_e32 v52, v52, v84
	v_mul_f32_e32 v84, v91, v94
	v_mul_f32_e32 v51, v51, v84
	ds_read_b128 v[84:87], v35 offset:20480
	ds_read_b128 v[88:91], v35 offset:21504
	s_waitcnt lgkmcnt(1)
	v_mul_f32_e32 v84, v94, v84
	v_mul_f32_e32 v86, v94, v86
	v_mul_f32_e32 v84, v48, v84
	v_mul_f32_e32 v48, v50, v86
	v_mul_f32_e32 v50, v94, v87
	v_mul_f32_e32 v47, v47, v50
	s_waitcnt lgkmcnt(0)
	v_mul_f32_e32 v50, v94, v88
	v_mul_f32_e32 v46, v46, v50
	v_mul_f32_e32 v50, v94, v89
	ds_read_b128 v[86:89], v35 offset:22528
	v_mul_f32_e32 v45, v45, v50
	v_mul_f32_e32 v50, v94, v90
	v_mul_f32_e32 v44, v44, v50
	v_mul_f32_e32 v50, v94, v91
	ds_read_b128 v[90:93], v35 offset:23552
	v_mul_f32_e32 v43, v43, v50
	s_waitcnt lgkmcnt(1)
	v_mul_f32_e32 v50, v94, v86
	v_mul_f32_e32 v42, v42, v50
	v_mul_f32_e32 v50, v94, v87
	v_mul_f32_e32 v41, v41, v50
	v_mul_f32_e32 v50, v94, v88
	v_mul_f32_e32 v85, v94, v85
	v_mul_f32_e32 v40, v40, v50
	v_mul_f32_e32 v50, v94, v89
	v_mul_f32_e32 v49, v49, v85
	v_mul_f32_e32 v85, v39, v50
	s_waitcnt lgkmcnt(0)
	v_mul_f32_e32 v39, v94, v90
	v_mul_f32_e32 v38, v38, v39
	v_mul_f32_e32 v39, v94, v91
	v_mul_f32_e32 v50, v81, v39
	v_mul_f32_e32 v39, v94, v92
	v_mul_f32_e32 v39, v80, v39
	v_mul_f32_e32 v80, v94, v93
	v_mul_f32_e32 v79, v79, v80
	ds_read_b128 v[86:89], v35 offset:24576
	ds_read_b128 v[90:93], v35 offset:25600
	s_waitcnt lgkmcnt(1)
	v_mul_f32_e32 v80, v94, v86
	v_mul_f32_e32 v81, v94, v87
	v_mul_f32_e32 v86, v94, v88
	v_mul_f32_e32 v80, v73, v80
	v_mul_f32_e32 v81, v77, v81
	v_mul_f32_e32 v77, v78, v86
	v_mul_f32_e32 v73, v94, v89
	ds_read_b128 v[86:89], v35 offset:26624
	v_mul_f32_e32 v75, v75, v73
	s_waitcnt lgkmcnt(1)
	v_mul_f32_e32 v73, v94, v90
	v_mul_f32_e32 v73, v74, v73
	v_mul_f32_e32 v74, v94, v91
	v_mul_f32_e32 v74, v76, v74
	v_mul_f32_e32 v76, v94, v92
	v_mul_f32_e32 v72, v72, v76
	v_mul_f32_e32 v76, v94, v93
	ds_read_b128 v[90:93], v35 offset:27648
	v_mul_f32_e32 v71, v71, v76
	s_waitcnt lgkmcnt(1)
	v_mul_f32_e32 v76, v94, v86
	v_mul_f32_e32 v68, v68, v76
	v_mul_f32_e32 v76, v94, v87
	v_mul_f32_e32 v70, v70, v76
	v_mul_f32_e32 v76, v94, v88
	v_mul_f32_e32 v69, v69, v76
	v_mul_f32_e32 v76, v94, v89
	v_mul_f32_e32 v76, v29, v76
	s_waitcnt lgkmcnt(0)
	v_mul_f32_e32 v29, v94, v90
	v_mul_f32_e32 v27, v27, v29
	v_mul_f32_e32 v29, v94, v91
	v_mul_f32_e32 v29, v67, v29
	v_mul_f32_e32 v67, v94, v92
	v_mul_f32_e32 v28, v28, v67
	v_mul_f32_e32 v67, v94, v93
	v_mul_f32_e32 v26, v26, v67
	ds_read_b128 v[86:89], v35 offset:28672
	ds_read_b128 v[90:93], v35 offset:29696
	s_waitcnt lgkmcnt(1)
	v_mul_f32_e32 v67, v94, v86
	v_mul_f32_e32 v86, v94, v88
	v_mul_f32_e32 v78, v94, v87
	v_mul_f32_e32 v67, v20, v67
	v_mul_f32_e32 v20, v23, v86
	v_mul_f32_e32 v23, v94, v89
	ds_read_b128 v[86:89], v35 offset:30720
	v_mul_f32_e32 v23, v19, v23
	s_waitcnt lgkmcnt(1)
	v_mul_f32_e32 v19, v94, v90
	v_mul_f32_e32 v18, v18, v19
	v_mul_f32_e32 v19, v94, v91
	v_mul_f32_e32 v19, v25, v19
	v_mul_f32_e32 v25, v94, v92
	v_mul_f32_e32 v21, v21, v25
	v_mul_f32_e32 v25, v94, v93
	ds_read_b128 v[90:93], v35 offset:31744
	v_mul_f32_e32 v16, v16, v25
	s_waitcnt lgkmcnt(1)
	v_mul_f32_e32 v25, v94, v86
	v_mul_f32_e32 v24, v24, v25
	v_mul_f32_e32 v25, v94, v87
	v_mul_f32_e32 v25, v17, v25
	v_mul_f32_e32 v17, v94, v88
	v_mul_f32_e32 v17, v14, v17
	v_mul_f32_e32 v14, v94, v89
	v_mul_f32_e32 v22, v22, v78
	v_mul_f32_e32 v78, v15, v14
	s_waitcnt lgkmcnt(0)
	v_mul_f32_e32 v14, v94, v90
	v_mul_f32_e32 v15, v94, v91
	v_mul_f32_e32 v14, v82, v14
	v_mul_f32_e32 v15, v12, v15
	v_mul_f32_e32 v12, v94, v92
	v_mul_f32_e32 v82, v94, v93
	v_mul_f32_e32 v12, v83, v12
	v_mul_f32_e32 v13, v13, v82
	v_max_f32_e64 v82, |v66|, |v65|
	v_max_f32_e64 v83, |v64|, |v63|
	v_max3_f32 v82, v82, 0, v83
	v_max_f32_e64 v83, |v62|, |v61|
	v_max_f32_e64 v86, |v60|, |v59|
	v_max3_f32 v82, v82, v83, v86
	v_max_f32_e64 v83, |v58|, |v57|
	v_max_f32_e64 v86, |v56|, |v55|
	v_max3_f32 v82, v82, v83, v86
	v_max_f32_e64 v83, |v54|, |v53|
	v_max_f32_e64 v86, |v52|, |v51|
	v_max3_f32 v82, v82, v83, v86
	v_max_f32_e64 v83, |v84|, |v49|
	v_max_f32_e64 v86, |v48|, |v47|
	v_max3_f32 v82, v82, v83, v86
	v_max_f32_e64 v83, |v46|, |v45|
	v_max_f32_e64 v86, |v44|, |v43|
	v_max3_f32 v82, v82, v83, v86
	v_max_f32_e64 v83, |v42|, |v41|
	v_max_f32_e64 v86, |v40|, |v85|
	v_max3_f32 v82, v82, v83, v86
	v_max_f32_e64 v83, |v38|, |v50|
	v_max_f32_e64 v86, |v39|, |v79|
	v_max3_f32 v82, v82, v83, v86
	v_max_f32_e64 v83, |v80|, |v81|
	v_max_f32_e64 v86, |v77|, |v75|
	v_max3_f32 v82, v82, v83, v86
	v_max_f32_e64 v83, |v73|, |v74|
	v_max_f32_e64 v86, |v72|, |v71|
	v_max3_f32 v82, v82, v83, v86
	v_max_f32_e64 v83, |v68|, |v70|
	v_max_f32_e64 v86, |v69|, |v76|
	v_max3_f32 v82, v82, v83, v86
	v_max_f32_e64 v83, |v27|, |v29|
	v_max_f32_e64 v86, |v28|, |v26|
	v_max3_f32 v82, v82, v83, v86
	v_max_f32_e64 v83, |v67|, |v22|
	v_max_f32_e64 v86, |v20|, |v23|
	v_max3_f32 v82, v82, v83, v86
	v_max_f32_e64 v83, |v18|, |v19|
	v_max_f32_e64 v86, |v21|, |v16|
	v_max3_f32 v82, v82, v83, v86
	v_max_f32_e64 v83, |v24|, |v25|
	v_max_f32_e64 v86, |v17|, |v78|
	v_max3_f32 v82, v82, v83, v86
	v_max_f32_e64 v83, |v14|, |v15|
	v_max_f32_e64 v86, |v12|, |v13|
	v_max3_f32 v82, v82, v83, v86
	ds_bpermute_b32 v83, v1, v82
	s_waitcnt lgkmcnt(0)
	v_max_f32_e32 v83, v83, v83
	v_max_f32_e32 v82, v82, v83
	ds_bpermute_b32 v83, v30, v82
	s_waitcnt lgkmcnt(0)
	v_max_f32_e32 v83, v83, v83
	v_max_f32_e32 v82, v82, v83
	ds_bpermute_b32 v83, v31, v82
	s_waitcnt lgkmcnt(0)
	v_max_f32_e32 v83, v83, v83
	v_max_f32_e32 v82, v82, v83
	ds_bpermute_b32 v83, v32, v82
	s_waitcnt lgkmcnt(0)
	v_max_f32_e32 v83, v83, v83
	v_max_f32_e32 v82, v82, v83
	ds_bpermute_b32 v83, v33, v82
	s_waitcnt lgkmcnt(0)
	v_max_f32_e32 v83, v83, v83
	v_max_f32_e32 v82, v82, v83
	ds_bpermute_b32 v83, v34, v82
	s_waitcnt lgkmcnt(0)
	v_max3_f32 v82, v82, v83, s47
	s_and_saveexec_b64 s[0:1], s[6:7]
	s_cbranch_execz .LBB0_1345
	s_lshl_b64 s[8:9], s[24:25], 2
	s_add_u32 s8, s26, s8
	v_mul_f32_e32 v83, 0x3c010204, v82
	s_addc_u32 s9, s27, s9
	global_store_dword v3, v83, s[8:9]

.LBB0_1672:
	s_or_b64 exec, exec, s[2:3]
	s_ashr_i32 s13, s12, 31
	s_lshl_b64 s[2:3], s[12:13], 13
	v_lshl_add_u64 v[0:1], v[18:19], 0, s[2:3]
	v_add_co_u32_e32 v12, vcc, 0x1000, v0
	global_load_dwordx2 v[2:3], v[0:1], off offset:512
	global_load_dwordx2 v[4:5], v[0:1], off offset:1024
	global_load_dwordx2 v[6:7], v[0:1], off offset:2048
	global_load_dwordx2 v[8:9], v[0:1], off offset:2560
	global_load_dwordx2 v[10:11], v[0:1], off offset:3072
	v_addc_co_u32_e32 v13, vcc, 0, v1, vcc
	global_load_dwordx2 v[14:15], v[12:13], off
	global_load_dwordx2 v[24:25], v[12:13], off offset:512
	v_lshl_add_u64 v[26:27], v[20:21], 0, s[2:3]
	global_load_dwordx2 v[28:29], v[12:13], off offset:1024
	global_load_dwordx2 v[78:79], v[0:1], off
	global_load_dwordx2 v[106:107], v[0:1], off offset:1536
	global_load_dwordx2 v[112:113], v[0:1], off offset:3584
	global_load_dwordx2 v[76:77], v[26:27], off nt
	global_load_dwordx2 v[86:87], v[26:27], off offset:512 nt
	global_load_dwordx2 v[94:95], v[26:27], off offset:1024 nt
	global_load_dwordx2 v[108:109], v[26:27], off offset:1536 nt
	global_load_dwordx2 v[30:31], v[12:13], off offset:2048
	global_load_dwordx2 v[102:103], v[26:27], off offset:2048 nt
	global_load_dwordx2 v[92:93], v[26:27], off offset:2560 nt
	global_load_dwordx2 v[100:101], v[26:27], off offset:3072 nt
	global_load_dwordx2 v[120:121], v[26:27], off offset:3584 nt
	global_load_dwordx2 v[38:39], v[12:13], off offset:2560
	v_add_co_u32_e32 v0, vcc, s22, v26
	s_lshl_b64 s[2:3], s[12:13], 14
	s_nop 0
	v_addc_co_u32_e32 v1, vcc, 0, v27, vcc
	global_load_dwordx2 v[114:115], v[0:1], off nt
	global_load_dwordx2 v[98:99], v[0:1], off offset:512 nt
	global_load_dwordx2 v[66:67], v[0:1], off offset:1024 nt
	global_load_dwordx2 v[64:65], v[0:1], off offset:1536 nt
	global_load_dwordx2 v[70:71], v[12:13], off offset:3072
	global_load_dwordx2 v[62:63], v[0:1], off offset:2048 nt
	global_load_dwordx2 v[60:61], v[0:1], off offset:2560 nt
	global_load_dwordx2 v[58:59], v[0:1], off offset:3072 nt
	global_load_dwordx2 v[56:57], v[0:1], off offset:3584 nt
	global_load_dwordx2 v[72:73], v[12:13], off offset:1536
	global_load_dwordx2 v[68:69], v[12:13], off offset:3584
	s_waitcnt vmcnt(24)
	v_readfirstlane_b32 s98, v223
	s_nop 1
	v_mov_b32_e32 v166, s98
	v_and_b32_e32 v35, 0xffff0000, v28
	v_lshlrev_b32_e32 v34, 16, v28
	v_and_b32_e32 v33, 0xffff0000, v29
	v_lshlrev_b32_e32 v32, 16, v29
	v_and_b32_e32 v51, 0xffff0000, v3
	v_and_b32_e32 v50, 0xffff0000, v2
	v_lshlrev_b32_e32 v13, 16, v3
	v_lshlrev_b32_e32 v12, 16, v2
	v_pk_mul_f32 v[0:1], v[50:51], v[50:51]
	s_waitcnt vmcnt(16)
	v_lshlrev_b32_e32 v85, 16, v31
	v_pk_fma_f32 v[0:1], v[12:13], v[12:13], v[0:1]
	v_and_b32_e32 v43, 0xffff0000, v15
	v_and_b32_e32 v42, 0xffff0000, v14
	v_lshlrev_b32_e32 v137, 16, v15
	v_lshlrev_b32_e32 v136, 16, v14
	v_pk_add_f32 v[126:127], v[0:1], v[0:1] op_sel:[0,1] op_sel_hi:[1,0]
	v_pk_mul_f32 v[0:1], v[42:43], v[42:43]
	v_and_b32_e32 v41, 0xffff0000, v25
	v_pk_fma_f32 v[0:1], v[136:137], v[136:137], v[0:1]
	v_and_b32_e32 v40, 0xffff0000, v24
	v_pk_add_f32 v[140:141], v[0:1], v[0:1] op_sel:[0,1] op_sel_hi:[1,0]
	v_lshlrev_b32_e32 v169, 16, v25
	v_lshlrev_b32_e32 v168, 16, v24
	v_pk_mul_f32 v[0:1], v[40:41], v[40:41]
	v_lshlrev_b32_e32 v84, 16, v30
	v_pk_fma_f32 v[0:1], v[168:169], v[168:169], v[0:1]
	v_and_b32_e32 v31, 0xffff0000, v31
	v_pk_add_f32 v[156:157], v[0:1], v[0:1] op_sel:[0,1] op_sel_hi:[1,0]
	v_mul_f32_e32 v0, v35, v35
	v_pk_fma_f32 v[152:153], v[34:35], v[34:35], v[0:1] op_sel_hi:[1,1,0]
	v_mul_f32_e32 v0, v33, v33
	v_and_b32_e32 v30, 0xffff0000, v30
	v_pk_fma_f32 v[154:155], v[32:33], v[32:33], v[0:1] op_sel_hi:[1,1,0]
	v_pk_mul_f32 v[0:1], v[30:31], v[30:31]
	v_and_b32_e32 v37, 0xffff0000, v11
	v_pk_fma_f32 v[0:1], v[84:85], v[84:85], v[0:1]
	s_waitcnt vmcnt(11)
	v_and_b32_e32 v29, 0xffff0000, v39
	v_and_b32_e32 v28, 0xffff0000, v38
	v_lshlrev_b32_e32 v36, 16, v11
	v_mul_f32_e32 v26, v37, v37
	v_pk_add_f32 v[146:147], v[0:1], v[0:1] op_sel:[0,1] op_sel_hi:[1,0]
	v_lshlrev_b32_e32 v83, 16, v39
	v_lshlrev_b32_e32 v82, 16, v38
	v_pk_mul_f32 v[0:1], v[28:29], v[28:29]
	v_pk_fma_f32 v[130:131], v[36:37], v[36:37], v[26:27] op_sel_hi:[1,1,0]
	v_pk_fma_f32 v[0:1], v[82:83], v[82:83], v[0:1]
	s_waitcnt vmcnt(6)
	v_and_b32_e32 v27, 0xffff0000, v70
	v_pk_add_f32 v[150:151], v[0:1], v[0:1] op_sel:[0,1] op_sel_hi:[1,0]
	v_lshlrev_b32_e32 v26, 16, v70
	v_mul_f32_e32 v0, v27, v27
	v_and_b32_e32 v25, 0xffff0000, v71
	v_pk_fma_f32 v[144:145], v[26:27], v[26:27], v[0:1] op_sel_hi:[1,1,0]
	v_lshlrev_b32_e32 v24, 16, v71
	v_mul_f32_e32 v0, v25, v25
	v_and_b32_e32 v75, 0xffff0000, v78
	v_pk_fma_f32 v[148:149], v[24:25], v[24:25], v[0:1] op_sel_hi:[1,1,0]
	v_lshlrev_b32_e32 v74, 16, v78
	v_mul_f32_e32 v0, v75, v75
	v_lshlrev_b32_e32 v78, 16, v79
	v_and_b32_e32 v79, 0xffff0000, v79
	v_pk_fma_f32 v[128:129], v[74:75], v[74:75], v[0:1] op_sel_hi:[1,1,0]
	v_mul_f32_e32 v0, v79, v79
	v_and_b32_e32 v53, 0xffff0000, v4
	v_and_b32_e32 v55, 0xffff0000, v5
	v_pk_fma_f32 v[134:135], v[78:79], v[78:79], v[0:1] op_sel_hi:[1,1,0]
	v_lshlrev_b32_e32 v52, 16, v4
	v_lshlrev_b32_e32 v54, 16, v5
	v_mul_f32_e32 v2, v53, v53
	v_mul_f32_e32 v4, v55, v55
	v_and_b32_e32 v143, 0xffff0000, v106
	v_and_b32_e32 v142, s0, v106
	v_pk_add_f32 v[128:129], v[128:129], v[134:135]
	v_lshlrev_b32_e32 v134, 16, v107
	v_and_b32_e32 v135, 0xffff0000, v107
	v_pk_fma_f32 v[110:111], v[52:53], v[52:53], v[2:3] op_sel_hi:[1,1,0]
	v_pk_fma_f32 v[118:119], v[54:55], v[54:55], v[4:5] op_sel_hi:[1,1,0]
	v_lshlrev_b32_e32 v104, 16, v106
	v_mov_b32_e32 v105, v143
	v_pk_mul_f32 v[142:143], v[142:143], v[142:143]
	v_pk_mul_f32 v[106:107], v[134:135], v[134:135]
	v_and_b32_e32 v49, 0xffff0000, v7
	v_and_b32_e32 v48, 0xffff0000, v6
	v_mul_f32_e32 v129, v104, v104
	v_mov_b32_e32 v127, v143
	v_mov_b32_e32 v111, v106
	v_mov_b32_e32 v119, v107
	v_lshlrev_b32_e32 v117, 16, v7
	v_lshlrev_b32_e32 v116, 16, v6
	v_and_b32_e32 v47, 0xffff0000, v9
	v_and_b32_e32 v46, 0xffff0000, v8
	v_pk_mul_f32 v[6:7], v[48:49], v[48:49]
	v_pk_add_f32 v[126:127], v[128:129], v[126:127]
	v_pk_add_f32 v[106:107], v[110:111], v[118:119]
	v_lshlrev_b32_e32 v123, 16, v9
	v_lshlrev_b32_e32 v122, 16, v8
	v_pk_mul_f32 v[8:9], v[46:47], v[46:47]
	v_pk_fma_f32 v[2:3], v[116:117], v[116:117], v[6:7]
	v_pk_add_f32 v[106:107], v[126:127], v[106:107]
	v_pk_fma_f32 v[4:5], v[122:123], v[122:123], v[8:9]
	v_pk_add_f32 v[132:133], v[2:3], v[2:3] op_sel:[0,1] op_sel_hi:[1,0]
	v_pk_add_f32 v[170:171], v[106:107], v[106:107] op_sel:[0,1] op_sel_hi:[1,0]
	v_lshlrev_b32_e32 v106, 16, v112
	v_and_b32_e32 v107, 0xffff0000, v112
	v_pk_add_f32 v[138:139], v[4:5], v[4:5] op_sel:[0,1] op_sel_hi:[1,0]
	v_mov_b32_e32 v126, v122
	v_mov_b32_e32 v127, v46
	v_mov_b32_e32 v46, v123
	v_pk_mul_f32 v[122:123], v[106:107], v[106:107]
	v_pk_add_f32 v[132:133], v[170:171], v[132:133]
	v_and_b32_e32 v45, 0xffff0000, v10
	v_mov_b32_e32 v139, v123
	v_mov_b32_e32 v133, v122
	v_lshlrev_b32_e32 v44, 16, v10
	v_mul_f32_e32 v10, v45, v45
	v_pk_add_f32 v[138:139], v[132:133], v[138:139]
	v_lshlrev_b32_e32 v132, 16, v113
	v_and_b32_e32 v133, 0xffff0000, v113
	v_pk_fma_f32 v[124:125], v[44:45], v[44:45], v[10:11] op_sel_hi:[1,1,0]
	v_pk_mul_f32 v[112:113], v[132:133], v[132:133]
	v_lshl_add_u64 v[38:39], v[22:23], 0, s[2:3]
	v_mov_b32_e32 v125, v112
	v_mov_b32_e32 v131, v113
	v_pk_add_f32 v[112:113], v[124:125], v[130:131]
	v_lshlrev_b32_e32 v124, 16, v115
	v_pk_add_f32 v[112:113], v[138:139], v[112:113]
	v_and_b32_e32 v125, 0xffff0000, v115
	v_pk_add_f32 v[170:171], v[112:113], v[112:113] op_sel:[0,1] op_sel_hi:[1,0]
	v_lshlrev_b32_e32 v112, 16, v114
	v_and_b32_e32 v113, 0xffff0000, v114
	s_waitcnt vmcnt(1)
	v_lshlrev_b32_e32 v114, 16, v72
	v_and_b32_e32 v115, 0xffff0000, v72
	v_mov_b32_e32 v138, v136
	v_mov_b32_e32 v139, v42
	v_mov_b32_e32 v42, v137
	v_mov_b32_e32 v136, v168
	v_mov_b32_e32 v137, v40
	v_mov_b32_e32 v40, v169
	v_pk_mul_f32 v[168:169], v[114:115], v[114:115]
	v_pk_add_f32 v[140:141], v[170:171], v[140:141]
	v_mov_b32_e32 v157, v169
	v_mov_b32_e32 v141, v168
	v_pk_add_f32 v[156:157], v[140:141], v[156:157]
	v_lshlrev_b32_e32 v140, 16, v73
	v_and_b32_e32 v141, 0xffff0000, v73
	v_pk_mul_f32 v[72:73], v[140:141], v[140:141]
	ds_read_b128 v[4:7], v16
	ds_read_b128 v[0:3], v16 offset:1024
	v_mov_b32_e32 v153, v72
	v_mov_b32_e32 v155, v73
	v_pk_add_f32 v[72:73], v[152:153], v[154:155]
	s_waitcnt vmcnt(0)
	v_and_b32_e32 v155, 0xffff0000, v68
	v_pk_add_f32 v[72:73], v[156:157], v[72:73]
	v_and_b32_e32 v154, s0, v68
	v_pk_add_f32 v[152:153], v[72:73], v[72:73] op_sel:[0,1] op_sel_hi:[1,0]
	v_lshlrev_b32_e32 v72, 16, v68
	v_pk_mul_f32 v[156:157], v[154:155], v[154:155]
	v_pk_add_f32 v[146:147], v[152:153], v[146:147]
	v_mov_b32_e32 v151, v157
	v_mul_f32_e32 v147, v72, v72
	v_lshlrev_b32_e32 v68, 16, v69
	v_and_b32_e32 v69, 0xffff0000, v69
	v_pk_add_f32 v[146:147], v[146:147], v[150:151]
	v_pk_mul_f32 v[150:151], v[68:69], v[68:69]
	v_lshlrev_b32_e32 v70, 16, v76
	v_mov_b32_e32 v145, v150
	v_mov_b32_e32 v149, v151
	v_pk_add_f32 v[144:145], v[144:145], v[148:149]
	v_mov_b32_e32 v148, v84
	v_pk_add_f32 v[144:145], v[146:147], v[144:145]
	v_mov_b32_e32 v149, v30
	v_add_f32_e32 v73, v144, v145
	ds_bpermute_b32 v145, v158, v73
	v_mov_b32_e32 v30, v85
	v_lshlrev_b32_e32 v84, 16, v60
	v_and_b32_e32 v85, 0xffff0000, v60
	v_mov_b32_e32 v151, v28
	s_waitcnt lgkmcnt(0)
	v_add_f32_e32 v73, v73, v145
	ds_bpermute_b32 v147, v159, v73
	v_mov_b32_e32 v28, v83
	v_and_b32_e32 v83, 0xffff0000, v56
	v_and_b32_e32 v71, 0xffff0000, v76
	v_lshlrev_b32_e32 v76, 16, v77
	s_waitcnt lgkmcnt(0)
	v_add_f32_e32 v73, v73, v147
	ds_bpermute_b32 v150, v160, v73
	v_and_b32_e32 v77, 0xffff0000, v77
	v_mov_b32_e32 v88, v12
	v_mov_b32_e32 v89, v50
	v_lshlrev_b32_e32 v80, 16, v86
	s_waitcnt lgkmcnt(0)
	v_add_f32_e32 v73, v73, v150
	ds_bpermute_b32 v150, v161, v73
	v_and_b32_e32 v81, 0xffff0000, v86
	v_mov_b32_e32 v50, v13
	ds_read_b128 v[12:15], v16 offset:2048
	ds_read_b128 v[8:11], v16 offset:3072
	v_lshlrev_b32_e32 v86, 16, v87
	s_waitcnt lgkmcnt(2)
	v_add_f32_e32 v60, v73, v150
	ds_bpermute_b32 v73, v162, v60
	v_mov_b32_e32 v150, v82
	v_and_b32_e32 v87, 0xffff0000, v87
	v_lshlrev_b32_e32 v90, 16, v94
	v_and_b32_e32 v91, 0xffff0000, v94
	s_waitcnt lgkmcnt(0)
	v_add_f32_e32 v73, v60, v73
	ds_bpermute_b32 v82, v163, v73
	v_lshlrev_b32_e32 v94, 16, v95
	v_and_b32_e32 v95, 0xffff0000, v95
	v_lshlrev_b32_e32 v96, 16, v108
	v_and_b32_e32 v97, 0xffff0000, v108
	s_waitcnt lgkmcnt(0)
	v_add_f32_e32 v73, v73, v82
	v_fmamk_f32 v73, v73, 0x39800000, v164
	v_mul_f32_e32 v82, 0x4f800000, v73
	v_cmp_gt_f32_e32 vcc, s23, v73
	v_lshlrev_b32_e32 v128, 16, v109
	v_and_b32_e32 v129, 0xffff0000, v109
	v_cndmask_b32_e32 v73, v73, v82, vcc
	v_sqrt_f32_e32 v154, v73
	v_lshlrev_b32_e32 v82, 16, v56
	v_lshlrev_b32_e32 v110, 16, v102
	v_and_b32_e32 v111, 0xffff0000, v102
	v_add_u32_e32 v56, -1, v154
	v_fma_f32 v156, -v56, v154, v73
	v_cmp_ge_f32_e64 s[2:3], 0, v156
	v_add_u32_e32 v156, 1, v154
	v_mov_b32_e32 v142, v116
	v_cndmask_b32_e64 v56, v154, v56, s[2:3]
	v_fma_f32 v154, -v156, v154, v73
	v_cmp_lt_f32_e64 s[2:3], 0, v154
	v_mov_b32_e32 v143, v48
	v_lshlrev_b32_e32 v118, 16, v103
	v_cndmask_b32_e64 v56, v56, v156, s[2:3]
	v_mul_f32_e32 v154, 0x37800000, v56
	v_cndmask_b32_e32 v56, v56, v154, vcc
	v_cmp_class_f32_e32 vcc, v73, v165
	v_and_b32_e32 v119, 0xffff0000, v103
	v_mov_b32_e32 v48, v117
	v_cndmask_b32_e32 v154, v56, v73, vcc
	v_div_scale_f32 v156, s[2:3], v154, v154, 0.5
	v_rcp_f32_e32 v157, v156
	v_mov_b32_e32 v73, v155
	v_lshlrev_b32_e32 v116, 16, v92
	v_and_b32_e32 v117, 0xffff0000, v92
	v_fma_f32 v155, -v156, v157, 1.0
	v_fmac_f32_e32 v157, v155, v157
	v_div_scale_f32 v155, vcc, 0.5, v154, 0.5
	v_mul_f32_e32 v167, v155, v157
	v_fma_f32 v168, -v156, v167, v155
	v_fmac_f32_e32 v167, v168, v157
	v_fma_f32 v155, -v156, v167, v155
	v_div_fmas_f32 v155, v155, v157, v167
	v_div_fixup_f32 v154, v155, v154, 0.5
	v_pk_mul_f32 v[74:75], v[154:155], v[74:75] op_sel_hi:[0,1]
	v_pk_fma_f32 v[4:5], v[4:5], v[74:75], v[70:71]
	v_pk_mul_f32 v[70:71], v[154:155], v[78:79] op_sel_hi:[0,1]
	v_pk_fma_f32 v[6:7], v[6:7], v[70:71], v[76:77]
	global_store_dwordx4 v[38:39], v[4:7], off nt
	v_lshlrev_b32_e32 v108, 16, v93
	v_and_b32_e32 v109, 0xffff0000, v93
	v_pk_mul_f32 v[4:5], v[154:155], v[88:89] op_sel_hi:[0,1]
	v_pk_fma_f32 v[0:1], v[0:1], v[4:5], v[80:81]
	v_pk_mul_f32 v[4:5], v[154:155], v[50:51] op_sel_hi:[0,1]
	v_pk_fma_f32 v[2:3], v[2:3], v[4:5], v[86:87]
	global_store_dwordx4 v[38:39], v[0:3], off offset:1024 nt
	v_lshlrev_b32_e32 v92, 16, v100
	v_and_b32_e32 v93, 0xffff0000, v100
	v_pk_mul_f32 v[0:1], v[154:155], v[52:53] op_sel_hi:[0,1]
	v_pk_mul_f32 v[2:3], v[154:155], v[54:55] op_sel_hi:[0,1]
	v_pk_fma_f32 v[0:1], v[12:13], v[0:1], v[90:91]
	v_pk_fma_f32 v[2:3], v[14:15], v[2:3], v[94:95]
	global_store_dwordx4 v[38:39], v[0:3], off offset:2048 nt
	v_lshlrev_b32_e32 v100, 16, v101
	v_and_b32_e32 v101, 0xffff0000, v101
	v_pk_mul_f32 v[0:1], v[154:155], v[104:105] op_sel_hi:[0,1]
	v_pk_mul_f32 v[2:3], v[154:155], v[134:135] op_sel_hi:[0,1]
	v_pk_fma_f32 v[0:1], v[0:1], v[8:9], v[96:97]
	v_pk_fma_f32 v[2:3], v[2:3], v[10:11], v[128:129]
	v_lshlrev_b32_e32 v102, 16, v120
	v_and_b32_e32 v103, 0xffff0000, v120
	v_lshlrev_b32_e32 v122, 16, v121
	v_and_b32_e32 v123, 0xffff0000, v121
	v_lshlrev_b32_e32 v130, 16, v98
	v_and_b32_e32 v131, 0xffff0000, v98
	v_lshlrev_b32_e32 v120, 16, v99
	v_and_b32_e32 v121, 0xffff0000, v99
	v_lshlrev_b32_e32 v98, 16, v66
	v_and_b32_e32 v99, 0xffff0000, v66
	v_lshlrev_b32_e32 v66, 16, v67
	v_and_b32_e32 v67, 0xffff0000, v67
	v_lshlrev_b32_e32 v144, 16, v64
	v_and_b32_e32 v145, 0xffff0000, v64
	v_lshlrev_b32_e32 v64, 16, v65
	v_and_b32_e32 v65, 0xffff0000, v65
	v_lshlrev_b32_e32 v146, 16, v62
	v_and_b32_e32 v147, 0xffff0000, v62
	v_lshlrev_b32_e32 v62, 16, v63
	v_and_b32_e32 v63, 0xffff0000, v63
	v_lshlrev_b32_e32 v152, 16, v61
	v_and_b32_e32 v153, 0xffff0000, v61
	v_lshlrev_b32_e32 v60, 16, v58
	v_and_b32_e32 v61, 0xffff0000, v58
	v_lshlrev_b32_e32 v58, 16, v59
	v_and_b32_e32 v59, 0xffff0000, v59
	v_lshlrev_b32_e32 v56, 16, v57
	v_and_b32_e32 v57, 0xffff0000, v57
	global_store_dwordx4 v[38:39], v[0:3], off offset:3072 nt
	ds_read_b128 v[0:3], v16 offset:4096
	ds_read_b128 v[4:7], v16 offset:5120
	v_add_co_u32_e32 v12, vcc, s22, v38
	v_pk_mul_f32 v[8:9], v[154:155], v[142:143] op_sel_hi:[0,1]
	s_nop 0
	v_addc_co_u32_e32 v13, vcc, 0, v39, vcc
	v_pk_mul_f32 v[10:11], v[154:155], v[48:49] op_sel_hi:[0,1]
	v_add_co_u32_e32 v14, vcc, s24, v38
	s_waitcnt lgkmcnt(1)
	v_pk_fma_f32 v[0:1], v[8:9], v[0:1], v[110:111]
	v_pk_fma_f32 v[2:3], v[10:11], v[2:3], v[118:119]
	v_addc_co_u32_e32 v15, vcc, 0, v39, vcc
	global_store_dwordx4 v[14:15], v[0:3], off offset:-4096 nt
	ds_read_b128 v[8:11], v16 offset:6144
	s_nop 0
	v_pk_mul_f32 v[0:1], v[154:155], v[126:127] op_sel_hi:[0,1]
	v_pk_mul_f32 v[2:3], v[154:155], v[46:47] op_sel_hi:[0,1]
	s_waitcnt lgkmcnt(1)
	v_pk_fma_f32 v[0:1], v[0:1], v[4:5], v[116:117]
	v_pk_fma_f32 v[2:3], v[2:3], v[6:7], v[108:109]
	global_store_dwordx4 v[12:13], v[0:3], off offset:1024 nt
	ds_read_b128 v[0:3], v16 offset:7168
	v_pk_mul_f32 v[4:5], v[154:155], v[44:45] op_sel_hi:[0,1]
	v_pk_mul_f32 v[6:7], v[154:155], v[36:37] op_sel_hi:[0,1]
	s_waitcnt lgkmcnt(1)
	v_pk_fma_f32 v[4:5], v[4:5], v[8:9], v[92:93]
	v_pk_fma_f32 v[6:7], v[6:7], v[10:11], v[100:101]
	global_store_dwordx4 v[12:13], v[4:7], off offset:2048 nt
	s_nop 1
	v_pk_mul_f32 v[4:5], v[154:155], v[106:107] op_sel_hi:[0,1]
	s_waitcnt lgkmcnt(0)
	v_pk_fma_f32 v[0:1], v[4:5], v[0:1], v[102:103]
	v_pk_mul_f32 v[4:5], v[154:155], v[132:133] op_sel_hi:[0,1]
	v_pk_fma_f32 v[2:3], v[4:5], v[2:3], v[122:123]
	global_store_dwordx4 v[12:13], v[0:3], off offset:3072 nt
	ds_read_b128 v[0:3], v16 offset:8192
	ds_read_b128 v[4:7], v16 offset:9216
	v_pk_mul_f32 v[8:9], v[154:155], v[138:139] op_sel_hi:[0,1]
	v_pk_mul_f32 v[10:11], v[154:155], v[42:43] op_sel_hi:[0,1]
	s_waitcnt lgkmcnt(1)
	v_pk_fma_f32 v[0:1], v[8:9], v[0:1], v[112:113]
	v_pk_fma_f32 v[2:3], v[10:11], v[2:3], v[124:125]
	global_store_dwordx4 v[14:15], v[0:3], off nt
	ds_read_b128 v[8:11], v16 offset:10240
	s_nop 0
	v_pk_mul_f32 v[0:1], v[154:155], v[136:137] op_sel_hi:[0,1]
	v_pk_mul_f32 v[2:3], v[154:155], v[40:41] op_sel_hi:[0,1]
	s_waitcnt lgkmcnt(1)
	v_pk_fma_f32 v[0:1], v[0:1], v[4:5], v[130:131]
	v_pk_fma_f32 v[2:3], v[2:3], v[6:7], v[120:121]
	global_store_dwordx4 v[14:15], v[0:3], off offset:1024 nt
	ds_read_b128 v[0:3], v16 offset:11264
	v_pk_mul_f32 v[4:5], v[154:155], v[34:35] op_sel_hi:[0,1]
	v_pk_mul_f32 v[6:7], v[154:155], v[32:33] op_sel_hi:[0,1]
	s_waitcnt lgkmcnt(1)
	v_pk_fma_f32 v[4:5], v[4:5], v[8:9], v[98:99]
	v_pk_fma_f32 v[6:7], v[6:7], v[10:11], v[66:67]
	global_store_dwordx4 v[14:15], v[4:7], off offset:2048 nt
	s_nop 1
	v_pk_mul_f32 v[4:5], v[154:155], v[114:115] op_sel_hi:[0,1]
	s_waitcnt lgkmcnt(0)
	v_pk_fma_f32 v[0:1], v[4:5], v[0:1], v[144:145]
	v_pk_mul_f32 v[4:5], v[154:155], v[140:141] op_sel_hi:[0,1]
	v_pk_fma_f32 v[2:3], v[4:5], v[2:3], v[64:65]
	global_store_dwordx4 v[14:15], v[0:3], off offset:3072 nt
	ds_read_b128 v[0:3], v16 offset:12288
	ds_read_b128 v[4:7], v16 offset:13312
	v_pk_mul_f32 v[8:9], v[154:155], v[148:149] op_sel_hi:[0,1]
	v_pk_mul_f32 v[10:11], v[154:155], v[30:31] op_sel_hi:[0,1]
	v_add_co_u32_e32 v12, vcc, s25, v38
	s_waitcnt lgkmcnt(1)
	v_pk_fma_f32 v[0:1], v[8:9], v[0:1], v[146:147]
	v_pk_fma_f32 v[2:3], v[10:11], v[2:3], v[62:63]
	v_addc_co_u32_e32 v13, vcc, 0, v39, vcc
	global_store_dwordx4 v[12:13], v[0:3], off nt
	ds_read_b128 v[8:11], v16 offset:14336
	s_nop 0
	v_pk_mul_f32 v[0:1], v[154:155], v[150:151] op_sel_hi:[0,1]
	v_pk_mul_f32 v[2:3], v[154:155], v[28:29] op_sel_hi:[0,1]
	s_waitcnt lgkmcnt(1)
	v_pk_fma_f32 v[0:1], v[0:1], v[4:5], v[84:85]
	v_pk_fma_f32 v[2:3], v[2:3], v[6:7], v[152:153]
	global_store_dwordx4 v[12:13], v[0:3], off offset:1024 nt
	ds_read_b128 v[0:3], v16 offset:15360
	v_pk_mul_f32 v[4:5], v[154:155], v[26:27] op_sel_hi:[0,1]
	v_pk_mul_f32 v[6:7], v[154:155], v[24:25] op_sel_hi:[0,1]
	s_waitcnt lgkmcnt(1)
	v_pk_fma_f32 v[4:5], v[4:5], v[8:9], v[60:61]
	v_pk_fma_f32 v[6:7], v[6:7], v[10:11], v[58:59]
	global_store_dwordx4 v[12:13], v[4:7], off offset:2048 nt
	s_nop 1
	v_pk_mul_f32 v[4:5], v[154:155], v[72:73] op_sel_hi:[0,1]
	s_waitcnt lgkmcnt(0)
	v_pk_fma_f32 v[0:1], v[4:5], v[0:1], v[82:83]
	v_pk_mul_f32 v[4:5], v[154:155], v[68:69] op_sel_hi:[0,1]
	v_pk_fma_f32 v[2:3], v[4:5], v[2:3], v[56:57]
	global_store_dwordx4 v[12:13], v[0:3], off offset:3072 nt
	s_mov_b64 s[2:3], -1
	s_and_b64 vcc, exec, s[6:7]
	s_cbranch_vccz .LBB0_1676
	s_andn2_b64 vcc, exec, s[10:11]
	s_mov_b32 s13, s21
	s_cbranch_vccnz .LBB0_1675
	v_readfirstlane_b32 s2, v166
	s_lshl_b32 s2, s2, 3
	s_add_i32 s13, s20, s2
